# K-loop: As00/As10 restage pairs issued at the end of the MFMA segments (before their closing barrier) instead of in a load segment
# baseline (speedup 1.0000x reference)
.LBB0_175:
	s_mov_b32 m0, s55
	s_nop 0
	global_load_lds_dwordx4 v194, s[84:85]
	s_mov_b32 m0, s67
	s_nop 0
	global_load_lds_dwordx4 v196, s[84:85]
	s_barrier
	s_add_i32 s88, s88, 2
	s_add_u32 s79, s79, 0x240000
	s_addc_u32 s97, s97, 0
	s_add_u32 s80, s80, 0x460000
	s_addc_u32 s81, s81, 0
	s_cmp_gt_u32 s88, 29
	s_cbranch_scc1 .LBB0_184
.LBB0_176:
	v_add_u32_e32 v130, 0x10000, v243
	v_add_u32_e32 v142, 0x14000, v243
	ds_read_b128 v[146:149], v130
	ds_read_b128 v[150:153], v130 offset:1024
	ds_read_b128 v[154:157], v130 offset:2048
	ds_read_b128 v[158:161], v130 offset:3072
	ds_read_b128 v[130:133], v142
	ds_read_b128 v[134:137], v142 offset:1024
	ds_read_b128 v[138:141], v142 offset:2048
	ds_read_b128 v[142:145], v142 offset:3072
	v_lshl_add_u64 v[246:247], v[234:235], 0, s[80:81]
	s_add_i32 m0, s8, 0xc000
	s_waitcnt lgkmcnt(0)
	ds_read_b128 v[174:177], v244
	ds_read_b128 v[190:193], v244 offset:1024
	ds_read_b128 v[170:173], v244 offset:2048
	ds_read_b128 v[186:189], v244 offset:3072
	ds_read_b128 v[166:169], v244 offset:4096
	ds_read_b128 v[182:185], v244 offset:5120
	ds_read_b128 v[162:165], v244 offset:6144
	ds_read_b128 v[178:181], v244 offset:7168
	global_load_lds_dwordx4 v[246:247], off
	v_lshl_add_u64 v[246:247], v[236:237], 0, s[80:81]
	s_add_i32 m0, s8, 0xe000
	s_nop 0
	global_load_lds_dwordx4 v[246:247], off
	s_waitcnt vmcnt(8) lgkmcnt(0)
	s_barrier
	v_mfma_f32_16x16x32_bf16 v[118:121], v[146:149], v[174:177], v[118:121]
	v_mfma_f32_16x16x32_bf16 v[126:129], v[154:157], v[174:177], v[126:129]
	v_mfma_f32_16x16x32_bf16 v[102:105], v[146:149], v[170:173], v[102:105]
	v_mfma_f32_16x16x32_bf16 v[110:113], v[154:157], v[170:173], v[110:113]
	v_mfma_f32_16x16x32_bf16 v[86:89], v[146:149], v[166:169], v[86:89]
	v_mfma_f32_16x16x32_bf16 v[94:97], v[154:157], v[166:169], v[94:97]
	v_mfma_f32_16x16x32_bf16 v[70:73], v[146:149], v[162:165], v[70:73]
	v_mfma_f32_16x16x32_bf16 v[78:81], v[154:157], v[162:165], v[78:81]
	v_mfma_f32_16x16x32_bf16 v[118:121], v[150:153], v[190:193], v[118:121]
	v_mfma_f32_16x16x32_bf16 v[126:129], v[158:161], v[190:193], v[126:129]
	v_mfma_f32_16x16x32_bf16 v[102:105], v[150:153], v[186:189], v[102:105]
	v_mfma_f32_16x16x32_bf16 v[110:113], v[158:161], v[186:189], v[110:113]
	v_mfma_f32_16x16x32_bf16 v[86:89], v[150:153], v[182:185], v[86:89]
	v_mfma_f32_16x16x32_bf16 v[94:97], v[158:161], v[182:185], v[94:97]
	v_mfma_f32_16x16x32_bf16 v[70:73], v[150:153], v[178:181], v[70:73]
	v_mfma_f32_16x16x32_bf16 v[78:81], v[158:161], v[178:181], v[78:81]
	v_mfma_f32_16x16x32_bf16 v[122:125], v[130:133], v[174:177], v[122:125]
	v_mfma_f32_16x16x32_bf16 v[114:117], v[138:141], v[174:177], v[114:117]
	v_mfma_f32_16x16x32_bf16 v[106:109], v[130:133], v[170:173], v[106:109]
	v_mfma_f32_16x16x32_bf16 v[98:101], v[138:141], v[170:173], v[98:101]
	v_mfma_f32_16x16x32_bf16 v[90:93], v[130:133], v[166:169], v[90:93]
	v_mfma_f32_16x16x32_bf16 v[82:85], v[138:141], v[166:169], v[82:85]
	v_mfma_f32_16x16x32_bf16 v[74:77], v[130:133], v[162:165], v[74:77]
	v_mfma_f32_16x16x32_bf16 v[66:69], v[138:141], v[162:165], v[66:69]
	v_mfma_f32_16x16x32_bf16 v[122:125], v[134:137], v[190:193], v[122:125]
	v_mfma_f32_16x16x32_bf16 v[114:117], v[142:145], v[190:193], v[114:117]
	v_mfma_f32_16x16x32_bf16 v[106:109], v[134:137], v[186:189], v[106:109]
	v_mfma_f32_16x16x32_bf16 v[98:101], v[142:145], v[186:189], v[98:101]
	v_mfma_f32_16x16x32_bf16 v[90:93], v[134:137], v[182:185], v[90:93]
	v_mfma_f32_16x16x32_bf16 v[82:85], v[142:145], v[182:185], v[82:85]
	v_mfma_f32_16x16x32_bf16 v[74:77], v[134:137], v[178:181], v[74:77]
	v_mfma_f32_16x16x32_bf16 v[66:69], v[142:145], v[178:181], v[66:69]
	s_barrier
	s_andn2_b64 s[48:49], exec, s[50:51]
	s_andn2_b64 vcc, exec, s[50:51]
	s_cbranch_vccnz .LBB0_178
	ds_read_b128 v[174:177], v244 offset:16384
	ds_read_b128 v[190:193], v244 offset:17408
	ds_read_b128 v[170:173], v244 offset:18432
	ds_read_b128 v[186:189], v244 offset:19456
	ds_read_b128 v[166:169], v244 offset:20480
	ds_read_b128 v[182:185], v244 offset:21504
	ds_read_b128 v[162:165], v244 offset:22528
	ds_read_b128 v[178:181], v244 offset:23552
.LBB0_178:
	s_add_u32 s82, s0, s80
	s_addc_u32 s83, s1, s81
	s_add_u32 s84, s82, 0x460000
	s_addc_u32 s85, s83, 0
	s_cmp_eq_u32 s80, 0x41a0000
	s_cselect_b64 s[86:87], -1, 0
	s_and_b64 s[82:83], s[86:87], exec
	s_cselect_b32 s83, s71, s97
	s_cselect_b32 s82, s73, s79
	s_mov_b32 m0, s9
	s_cselect_b32 s85, s22, s85
	s_cselect_b32 s84, s69, s84
	s_add_u32 vcc_lo, s82, 0x4000
	global_load_lds_dwordx4 v194, s[82:83]
	s_mov_b32 m0, s10
	s_addc_u32 vcc_hi, s83, 0
	global_load_lds_dwordx4 v196, s[82:83]
	s_mov_b32 m0, s11
	s_nop 0
	global_load_lds_dwordx4 v194, vcc
	v_lshl_add_u64 v[246:247], vcc, 0, v[196:197]
	s_mov_b32 m0, s12
	s_and_b64 vcc, exec, s[48:49]
	global_load_lds_dwordx4 v[246:247], off
	s_waitcnt vmcnt(6) lgkmcnt(0)
	s_barrier
	s_cbranch_vccnz .LBB0_180
	s_waitcnt lgkmcnt(0)
	v_mfma_f32_16x16x32_bf16 v[54:57], v[146:149], v[174:177], v[54:57]
	v_mfma_f32_16x16x32_bf16 v[62:65], v[154:157], v[174:177], v[62:65]
	v_mfma_f32_16x16x32_bf16 v[38:41], v[146:149], v[170:173], v[38:41]
	v_mfma_f32_16x16x32_bf16 v[46:49], v[154:157], v[170:173], v[46:49]
	v_mfma_f32_16x16x32_bf16 v[22:25], v[146:149], v[166:169], v[22:25]
	v_mfma_f32_16x16x32_bf16 v[30:33], v[154:157], v[166:169], v[30:33]
	v_mfma_f32_16x16x32_bf16 v[10:13], v[146:149], v[162:165], v[10:13]
	v_mfma_f32_16x16x32_bf16 v[14:17], v[154:157], v[162:165], v[14:17]
	v_mfma_f32_16x16x32_bf16 v[54:57], v[150:153], v[190:193], v[54:57]
	v_mfma_f32_16x16x32_bf16 v[62:65], v[158:161], v[190:193], v[62:65]
	v_mfma_f32_16x16x32_bf16 v[38:41], v[150:153], v[186:189], v[38:41]
	v_mfma_f32_16x16x32_bf16 v[46:49], v[158:161], v[186:189], v[46:49]
	v_mfma_f32_16x16x32_bf16 v[22:25], v[150:153], v[182:185], v[22:25]
	v_mfma_f32_16x16x32_bf16 v[30:33], v[158:161], v[182:185], v[30:33]
	v_mfma_f32_16x16x32_bf16 v[10:13], v[150:153], v[178:181], v[10:13]
	v_mfma_f32_16x16x32_bf16 v[14:17], v[158:161], v[178:181], v[14:17]
	v_mfma_f32_16x16x32_bf16 v[58:61], v[130:133], v[174:177], v[58:61]
	v_mfma_f32_16x16x32_bf16 v[50:53], v[138:141], v[174:177], v[50:53]
	v_mfma_f32_16x16x32_bf16 v[42:45], v[130:133], v[170:173], v[42:45]
	v_mfma_f32_16x16x32_bf16 v[34:37], v[138:141], v[170:173], v[34:37]
	v_mfma_f32_16x16x32_bf16 v[26:29], v[130:133], v[166:169], v[26:29]
	v_mfma_f32_16x16x32_bf16 v[18:21], v[138:141], v[166:169], v[18:21]
	v_mfma_f32_16x16x32_bf16 v[6:9], v[130:133], v[162:165], v[6:9]
	v_mfma_f32_16x16x32_bf16 v[2:5], v[138:141], v[162:165], v[2:5]
	v_mfma_f32_16x16x32_bf16 v[58:61], v[134:137], v[190:193], v[58:61]
	v_mfma_f32_16x16x32_bf16 v[50:53], v[142:145], v[190:193], v[50:53]
	v_mfma_f32_16x16x32_bf16 v[42:45], v[134:137], v[186:189], v[42:45]
	v_mfma_f32_16x16x32_bf16 v[34:37], v[142:145], v[186:189], v[34:37]
	v_mfma_f32_16x16x32_bf16 v[26:29], v[134:137], v[182:185], v[26:29]
	v_mfma_f32_16x16x32_bf16 v[18:21], v[142:145], v[182:185], v[18:21]
	v_mfma_f32_16x16x32_bf16 v[6:9], v[134:137], v[178:181], v[6:9]
	v_mfma_f32_16x16x32_bf16 v[2:5], v[142:145], v[178:181], v[2:5]
.LBB0_180:
	s_and_b64 vcc, s[46:47], s[86:87]
	v_cndmask_b32_e64 v131, v233, 0, vcc
	v_cndmask_b32_e32 v130, v232, v198, vcc
	v_lshl_add_u64 v[246:247], s[84:85], 0, v[130:131]
	s_mov_b32 m0, s8
	s_nop 0
	global_load_lds_dwordx4 v194, s[84:85]
	s_mov_b32 m0, s13
	s_nop 0
	global_load_lds_dwordx4 v196, s[84:85]
	s_barrier
	v_add_u32_e32 v130, 0x18000, v243
	v_add_u32_e32 v142, 0x1c000, v243
	ds_read_b128 v[146:149], v130
	ds_read_b128 v[150:153], v130 offset:1024
	ds_read_b128 v[154:157], v130 offset:2048
	ds_read_b128 v[158:161], v130 offset:3072
	ds_read_b128 v[130:133], v142
	ds_read_b128 v[134:137], v142 offset:1024
	ds_read_b128 v[138:141], v142 offset:2048
	ds_read_b128 v[142:145], v142 offset:3072
	s_mov_b32 m0, s14
	v_lshl_add_u64 v[248:249], v[246:247], 0, v[194:195]
	s_waitcnt lgkmcnt(0)
	ds_read_b128 v[174:177], v244 offset:32768
	ds_read_b128 v[190:193], v244 offset:33792
	ds_read_b128 v[170:173], v244 offset:34816
	ds_read_b128 v[186:189], v244 offset:35840
	ds_read_b128 v[166:169], v244 offset:36864
	ds_read_b128 v[182:185], v244 offset:37888
	ds_read_b128 v[162:165], v244 offset:38912
	ds_read_b128 v[178:181], v244 offset:39936
	global_load_lds_dwordx4 v[248:249], off
	v_lshl_add_u64 v[246:247], v[246:247], 0, v[196:197]
	s_mov_b32 m0, s15
	s_nop 0
	global_load_lds_dwordx4 v[246:247], off
	s_waitcnt vmcnt(8) lgkmcnt(0)
	s_barrier
	v_mfma_f32_16x16x32_bf16 v[118:121], v[146:149], v[174:177], v[118:121]
	v_mfma_f32_16x16x32_bf16 v[126:129], v[154:157], v[174:177], v[126:129]
	v_mfma_f32_16x16x32_bf16 v[102:105], v[146:149], v[170:173], v[102:105]
	v_mfma_f32_16x16x32_bf16 v[110:113], v[154:157], v[170:173], v[110:113]
	v_mfma_f32_16x16x32_bf16 v[86:89], v[146:149], v[166:169], v[86:89]
	v_mfma_f32_16x16x32_bf16 v[94:97], v[154:157], v[166:169], v[94:97]
	v_mfma_f32_16x16x32_bf16 v[70:73], v[146:149], v[162:165], v[70:73]
	v_mfma_f32_16x16x32_bf16 v[78:81], v[154:157], v[162:165], v[78:81]
	v_mfma_f32_16x16x32_bf16 v[118:121], v[150:153], v[190:193], v[118:121]
	v_mfma_f32_16x16x32_bf16 v[126:129], v[158:161], v[190:193], v[126:129]
	v_mfma_f32_16x16x32_bf16 v[102:105], v[150:153], v[186:189], v[102:105]
	v_mfma_f32_16x16x32_bf16 v[110:113], v[158:161], v[186:189], v[110:113]
	v_mfma_f32_16x16x32_bf16 v[86:89], v[150:153], v[182:185], v[86:89]
	v_mfma_f32_16x16x32_bf16 v[94:97], v[158:161], v[182:185], v[94:97]
	v_mfma_f32_16x16x32_bf16 v[70:73], v[150:153], v[178:181], v[70:73]
	v_mfma_f32_16x16x32_bf16 v[78:81], v[158:161], v[178:181], v[78:81]
	v_mfma_f32_16x16x32_bf16 v[122:125], v[130:133], v[174:177], v[122:125]
	v_mfma_f32_16x16x32_bf16 v[114:117], v[138:141], v[174:177], v[114:117]
	v_mfma_f32_16x16x32_bf16 v[106:109], v[130:133], v[170:173], v[106:109]
	v_mfma_f32_16x16x32_bf16 v[98:101], v[138:141], v[170:173], v[98:101]
	v_mfma_f32_16x16x32_bf16 v[90:93], v[130:133], v[166:169], v[90:93]
	v_mfma_f32_16x16x32_bf16 v[82:85], v[138:141], v[166:169], v[82:85]
	v_mfma_f32_16x16x32_bf16 v[74:77], v[130:133], v[162:165], v[74:77]
	v_mfma_f32_16x16x32_bf16 v[66:69], v[138:141], v[162:165], v[66:69]
	v_mfma_f32_16x16x32_bf16 v[122:125], v[134:137], v[190:193], v[122:125]
	v_mfma_f32_16x16x32_bf16 v[114:117], v[142:145], v[190:193], v[114:117]
	v_mfma_f32_16x16x32_bf16 v[106:109], v[134:137], v[186:189], v[106:109]
	v_mfma_f32_16x16x32_bf16 v[98:101], v[142:145], v[186:189], v[98:101]
	v_mfma_f32_16x16x32_bf16 v[90:93], v[134:137], v[182:185], v[90:93]
	v_mfma_f32_16x16x32_bf16 v[82:85], v[142:145], v[182:185], v[82:85]
	v_mfma_f32_16x16x32_bf16 v[74:77], v[134:137], v[178:181], v[74:77]
	v_mfma_f32_16x16x32_bf16 v[66:69], v[142:145], v[178:181], v[66:69]
	s_barrier
	s_and_b64 vcc, exec, s[48:49]
	s_cbranch_vccnz .LBB0_182
	ds_read_b128 v[174:177], v244 offset:49152
	ds_read_b128 v[190:193], v244 offset:50176
	ds_read_b128 v[170:173], v244 offset:51200
	ds_read_b128 v[186:189], v244 offset:52224
	ds_read_b128 v[166:169], v244 offset:53248
	ds_read_b128 v[182:185], v244 offset:54272
	ds_read_b128 v[162:165], v244 offset:55296
	ds_read_b128 v[178:181], v244 offset:56320
.LBB0_182:
	s_add_u32 s86, s82, 0x120000
	s_addc_u32 s87, s83, 0
	s_add_u32 s84, s84, 0x230000
	s_addc_u32 s85, s85, 0
	s_mov_b32 m0, s17
	s_add_u32 s82, s82, 0x124000
	global_load_lds_dwordx4 v194, s[86:87]
	s_mov_b32 m0, s54
	s_addc_u32 s83, s83, 0
	global_load_lds_dwordx4 v196, s[86:87]
	s_mov_b32 m0, s89
	s_and_b64 vcc, exec, s[48:49]
	global_load_lds_dwordx4 v194, s[82:83]
	s_mov_b32 m0, s90
	s_nop 0
	global_load_lds_dwordx4 v196, s[82:83]
	s_waitcnt vmcnt(6) lgkmcnt(0)
	s_barrier
	s_cbranch_vccnz .LBB0_175
	s_waitcnt lgkmcnt(0)
	v_mfma_f32_16x16x32_bf16 v[54:57], v[146:149], v[174:177], v[54:57]
	v_mfma_f32_16x16x32_bf16 v[62:65], v[154:157], v[174:177], v[62:65]
	v_mfma_f32_16x16x32_bf16 v[38:41], v[146:149], v[170:173], v[38:41]
	v_mfma_f32_16x16x32_bf16 v[46:49], v[154:157], v[170:173], v[46:49]
	v_mfma_f32_16x16x32_bf16 v[22:25], v[146:149], v[166:169], v[22:25]
	v_mfma_f32_16x16x32_bf16 v[30:33], v[154:157], v[166:169], v[30:33]
	v_mfma_f32_16x16x32_bf16 v[10:13], v[146:149], v[162:165], v[10:13]
	v_mfma_f32_16x16x32_bf16 v[14:17], v[154:157], v[162:165], v[14:17]
	v_mfma_f32_16x16x32_bf16 v[54:57], v[150:153], v[190:193], v[54:57]
	v_mfma_f32_16x16x32_bf16 v[62:65], v[158:161], v[190:193], v[62:65]
	v_mfma_f32_16x16x32_bf16 v[38:41], v[150:153], v[186:189], v[38:41]
	v_mfma_f32_16x16x32_bf16 v[46:49], v[158:161], v[186:189], v[46:49]
	v_mfma_f32_16x16x32_bf16 v[22:25], v[150:153], v[182:185], v[22:25]
	v_mfma_f32_16x16x32_bf16 v[30:33], v[158:161], v[182:185], v[30:33]
	v_mfma_f32_16x16x32_bf16 v[10:13], v[150:153], v[178:181], v[10:13]
	v_mfma_f32_16x16x32_bf16 v[14:17], v[158:161], v[178:181], v[14:17]
	v_mfma_f32_16x16x32_bf16 v[58:61], v[130:133], v[174:177], v[58:61]
	v_mfma_f32_16x16x32_bf16 v[50:53], v[138:141], v[174:177], v[50:53]
	v_mfma_f32_16x16x32_bf16 v[42:45], v[130:133], v[170:173], v[42:45]
	v_mfma_f32_16x16x32_bf16 v[34:37], v[138:141], v[170:173], v[34:37]
	v_mfma_f32_16x16x32_bf16 v[26:29], v[130:133], v[166:169], v[26:29]
	v_mfma_f32_16x16x32_bf16 v[18:21], v[138:141], v[166:169], v[18:21]
	v_mfma_f32_16x16x32_bf16 v[6:9], v[130:133], v[162:165], v[6:9]
	v_mfma_f32_16x16x32_bf16 v[2:5], v[138:141], v[162:165], v[2:5]
	v_mfma_f32_16x16x32_bf16 v[58:61], v[134:137], v[190:193], v[58:61]
	v_mfma_f32_16x16x32_bf16 v[50:53], v[142:145], v[190:193], v[50:53]
	v_mfma_f32_16x16x32_bf16 v[42:45], v[134:137], v[186:189], v[42:45]
	v_mfma_f32_16x16x32_bf16 v[34:37], v[142:145], v[186:189], v[34:37]
	v_mfma_f32_16x16x32_bf16 v[26:29], v[134:137], v[182:185], v[26:29]
	v_mfma_f32_16x16x32_bf16 v[18:21], v[142:145], v[182:185], v[18:21]
	v_mfma_f32_16x16x32_bf16 v[6:9], v[134:137], v[178:181], v[6:9]
	v_mfma_f32_16x16x32_bf16 v[2:5], v[142:145], v[178:181], v[2:5]
	s_branch .LBB0_175

.LBB0_558:
	s_mov_b32 m0, s55
	s_nop 0
	global_load_lds_dwordx4 v194, s[62:63]
	s_mov_b32 m0, s67
	s_nop 0
	global_load_lds_dwordx4 v196, s[62:63]
	s_barrier
	s_add_i32 s73, s73, 2
	s_add_u32 s53, s53, 0x80000
	s_addc_u32 s72, s72, 0
	s_add_u32 s58, s58, 0x440000
	s_addc_u32 s59, s59, 0
	s_cmp_gt_u32 s73, 29
	s_cbranch_scc1 .LBB0_567
.LBB0_559:
	ds_read_b128 v[146:149], v227
	ds_read_b128 v[150:153], v227 offset:1024
	ds_read_b128 v[154:157], v227 offset:2048
	ds_read_b128 v[158:161], v227 offset:3072
	ds_read_b128 v[130:133], v228
	ds_read_b128 v[134:137], v228 offset:1024
	ds_read_b128 v[138:141], v228 offset:2048
	ds_read_b128 v[142:145], v228 offset:3072
	v_lshl_add_u64 v[234:235], v[216:217], 0, s[58:59]
	s_add_i32 m0, s8, 0xc000
	s_waitcnt lgkmcnt(0)
	ds_read_b128 v[174:177], v229
	ds_read_b128 v[190:193], v229 offset:1024
	ds_read_b128 v[170:173], v229 offset:2048
	ds_read_b128 v[186:189], v229 offset:3072
	ds_read_b128 v[166:169], v229 offset:4096
	ds_read_b128 v[182:185], v229 offset:5120
	ds_read_b128 v[162:165], v229 offset:6144
	ds_read_b128 v[178:181], v229 offset:7168
	global_load_lds_dwordx4 v[234:235], off
	v_lshl_add_u64 v[234:235], v[218:219], 0, s[58:59]
	s_add_i32 m0, s8, 0xe000
	s_nop 0
	global_load_lds_dwordx4 v[234:235], off
	s_waitcnt vmcnt(8) lgkmcnt(0)
	s_barrier
	v_mfma_f32_16x16x32_bf16 v[126:129], v[146:149], v[174:177], v[126:129]
	v_mfma_f32_16x16x32_bf16 v[122:125], v[154:157], v[174:177], v[122:125]
	v_mfma_f32_16x16x32_bf16 v[110:113], v[146:149], v[170:173], v[110:113]
	v_mfma_f32_16x16x32_bf16 v[106:109], v[154:157], v[170:173], v[106:109]
	v_mfma_f32_16x16x32_bf16 v[94:97], v[146:149], v[166:169], v[94:97]
	v_mfma_f32_16x16x32_bf16 v[90:93], v[154:157], v[166:169], v[90:93]
	v_mfma_f32_16x16x32_bf16 v[78:81], v[146:149], v[162:165], v[78:81]
	v_mfma_f32_16x16x32_bf16 v[74:77], v[154:157], v[162:165], v[74:77]
	v_mfma_f32_16x16x32_bf16 v[126:129], v[150:153], v[190:193], v[126:129]
	v_mfma_f32_16x16x32_bf16 v[122:125], v[158:161], v[190:193], v[122:125]
	v_mfma_f32_16x16x32_bf16 v[110:113], v[150:153], v[186:189], v[110:113]
	v_mfma_f32_16x16x32_bf16 v[106:109], v[158:161], v[186:189], v[106:109]
	v_mfma_f32_16x16x32_bf16 v[94:97], v[150:153], v[182:185], v[94:97]
	v_mfma_f32_16x16x32_bf16 v[90:93], v[158:161], v[182:185], v[90:93]
	v_mfma_f32_16x16x32_bf16 v[78:81], v[150:153], v[178:181], v[78:81]
	v_mfma_f32_16x16x32_bf16 v[74:77], v[158:161], v[178:181], v[74:77]
	v_mfma_f32_16x16x32_bf16 v[118:121], v[130:133], v[174:177], v[118:121]
	v_mfma_f32_16x16x32_bf16 v[114:117], v[138:141], v[174:177], v[114:117]
	v_mfma_f32_16x16x32_bf16 v[102:105], v[130:133], v[170:173], v[102:105]
	v_mfma_f32_16x16x32_bf16 v[98:101], v[138:141], v[170:173], v[98:101]
	v_mfma_f32_16x16x32_bf16 v[86:89], v[130:133], v[166:169], v[86:89]
	v_mfma_f32_16x16x32_bf16 v[82:85], v[138:141], v[166:169], v[82:85]
	v_mfma_f32_16x16x32_bf16 v[70:73], v[130:133], v[162:165], v[70:73]
	v_mfma_f32_16x16x32_bf16 v[66:69], v[138:141], v[162:165], v[66:69]
	v_mfma_f32_16x16x32_bf16 v[118:121], v[134:137], v[190:193], v[118:121]
	v_mfma_f32_16x16x32_bf16 v[114:117], v[142:145], v[190:193], v[114:117]
	v_mfma_f32_16x16x32_bf16 v[102:105], v[134:137], v[186:189], v[102:105]
	v_mfma_f32_16x16x32_bf16 v[98:101], v[142:145], v[186:189], v[98:101]
	v_mfma_f32_16x16x32_bf16 v[86:89], v[134:137], v[182:185], v[86:89]
	v_mfma_f32_16x16x32_bf16 v[82:85], v[142:145], v[182:185], v[82:85]
	v_mfma_f32_16x16x32_bf16 v[70:73], v[134:137], v[178:181], v[70:73]
	v_mfma_f32_16x16x32_bf16 v[66:69], v[142:145], v[178:181], v[66:69]
	s_barrier
	v_cmp_ne_u32_e64 s[42:43], 1, v233
	s_andn2_b64 vcc, exec, s[44:45]
	s_cbranch_vccnz .LBB0_561
	ds_read_b128 v[174:177], v229 offset:16384
	ds_read_b128 v[190:193], v229 offset:17408
	ds_read_b128 v[170:173], v229 offset:18432
	ds_read_b128 v[186:189], v229 offset:19456
	ds_read_b128 v[166:169], v229 offset:20480
	ds_read_b128 v[182:185], v229 offset:21504
	ds_read_b128 v[162:165], v229 offset:22528
	ds_read_b128 v[178:181], v229 offset:23552
.LBB0_561:
	s_add_u32 s60, s56, s58
	s_addc_u32 s61, s57, s59
	s_add_u32 s62, s60, 0x440000
	s_addc_u32 s63, s61, 0
	s_cmp_eq_u32 s58, 0x3fc0000
	s_cselect_b64 s[68:69], -1, 0
	s_and_b64 s[60:61], s[68:69], exec
	s_cselect_b32 s61, s37, s72
	s_cselect_b32 s60, s47, s53
	s_mov_b32 m0, s9
	s_cselect_b32 s63, s1, s63
	s_cselect_b32 s62, s24, s62
	s_add_u32 s74, s60, 0x4000
	global_load_lds_dwordx4 v194, s[60:61]
	s_mov_b32 m0, s10
	s_addc_u32 s75, s61, 0
	global_load_lds_dwordx4 v196, s[60:61]
	s_mov_b32 m0, s11
	s_and_b64 vcc, exec, s[42:43]
	global_load_lds_dwordx4 v194, s[74:75]
	s_mov_b32 m0, s12
	s_nop 0
	global_load_lds_dwordx4 v196, s[74:75]
	s_waitcnt vmcnt(6) lgkmcnt(0)
	s_barrier
	s_cbranch_vccnz .LBB0_563
	s_waitcnt lgkmcnt(0)
	v_mfma_f32_16x16x32_bf16 v[62:65], v[146:149], v[174:177], v[62:65]
	v_mfma_f32_16x16x32_bf16 v[58:61], v[154:157], v[174:177], v[58:61]
	v_mfma_f32_16x16x32_bf16 v[46:49], v[146:149], v[170:173], v[46:49]
	v_mfma_f32_16x16x32_bf16 v[42:45], v[154:157], v[170:173], v[42:45]
	v_mfma_f32_16x16x32_bf16 v[30:33], v[146:149], v[166:169], v[30:33]
	v_mfma_f32_16x16x32_bf16 v[26:29], v[154:157], v[166:169], v[26:29]
	v_mfma_f32_16x16x32_bf16 v[14:17], v[146:149], v[162:165], v[14:17]
	v_mfma_f32_16x16x32_bf16 v[10:13], v[154:157], v[162:165], v[10:13]
	v_mfma_f32_16x16x32_bf16 v[62:65], v[150:153], v[190:193], v[62:65]
	v_mfma_f32_16x16x32_bf16 v[58:61], v[158:161], v[190:193], v[58:61]
	v_mfma_f32_16x16x32_bf16 v[46:49], v[150:153], v[186:189], v[46:49]
	v_mfma_f32_16x16x32_bf16 v[42:45], v[158:161], v[186:189], v[42:45]
	v_mfma_f32_16x16x32_bf16 v[30:33], v[150:153], v[182:185], v[30:33]
	v_mfma_f32_16x16x32_bf16 v[26:29], v[158:161], v[182:185], v[26:29]
	v_mfma_f32_16x16x32_bf16 v[14:17], v[150:153], v[178:181], v[14:17]
	v_mfma_f32_16x16x32_bf16 v[10:13], v[158:161], v[178:181], v[10:13]
	v_mfma_f32_16x16x32_bf16 v[54:57], v[130:133], v[174:177], v[54:57]
	v_mfma_f32_16x16x32_bf16 v[50:53], v[138:141], v[174:177], v[50:53]
	v_mfma_f32_16x16x32_bf16 v[38:41], v[130:133], v[170:173], v[38:41]
	v_mfma_f32_16x16x32_bf16 v[34:37], v[138:141], v[170:173], v[34:37]
	v_mfma_f32_16x16x32_bf16 v[22:25], v[130:133], v[166:169], v[22:25]
	v_mfma_f32_16x16x32_bf16 v[18:21], v[138:141], v[166:169], v[18:21]
	v_mfma_f32_16x16x32_bf16 v[6:9], v[130:133], v[162:165], v[6:9]
	v_mfma_f32_16x16x32_bf16 v[2:5], v[138:141], v[162:165], v[2:5]
	v_mfma_f32_16x16x32_bf16 v[54:57], v[134:137], v[190:193], v[54:57]
	v_mfma_f32_16x16x32_bf16 v[50:53], v[142:145], v[190:193], v[50:53]
	v_mfma_f32_16x16x32_bf16 v[38:41], v[134:137], v[186:189], v[38:41]
	v_mfma_f32_16x16x32_bf16 v[34:37], v[142:145], v[186:189], v[34:37]
	v_mfma_f32_16x16x32_bf16 v[22:25], v[134:137], v[182:185], v[22:25]
	v_mfma_f32_16x16x32_bf16 v[18:21], v[142:145], v[182:185], v[18:21]
	v_mfma_f32_16x16x32_bf16 v[6:9], v[134:137], v[178:181], v[6:9]
	v_mfma_f32_16x16x32_bf16 v[2:5], v[142:145], v[178:181], v[2:5]
.LBB0_563:
	s_and_b64 vcc, s[40:41], s[68:69]
	v_cndmask_b32_e64 v131, v215, 0, vcc
	v_cndmask_b32_e32 v130, v214, v198, vcc
	v_lshl_add_u64 v[234:235], s[62:63], 0, v[130:131]
	s_mov_b32 m0, s8
	s_nop 0
	global_load_lds_dwordx4 v194, s[62:63]
	s_mov_b32 m0, s13
	s_nop 0
	global_load_lds_dwordx4 v196, s[62:63]
	s_barrier
	v_add_u32_e32 v130, 0x18000, v226
	v_add_u32_e32 v142, 0x1c000, v226
	ds_read_b128 v[146:149], v130
	ds_read_b128 v[150:153], v130 offset:1024
	ds_read_b128 v[154:157], v130 offset:2048
	ds_read_b128 v[158:161], v130 offset:3072
	ds_read_b128 v[130:133], v142
	ds_read_b128 v[134:137], v142 offset:1024
	ds_read_b128 v[138:141], v142 offset:2048
	ds_read_b128 v[142:145], v142 offset:3072
	s_mov_b32 m0, s14
	v_lshl_add_u64 v[236:237], v[234:235], 0, v[194:195]
	s_waitcnt lgkmcnt(0)
	ds_read_b128 v[174:177], v229 offset:32768
	ds_read_b128 v[190:193], v229 offset:33792
	ds_read_b128 v[170:173], v229 offset:34816
	ds_read_b128 v[186:189], v229 offset:35840
	ds_read_b128 v[166:169], v229 offset:36864
	ds_read_b128 v[182:185], v229 offset:37888
	ds_read_b128 v[162:165], v229 offset:38912
	ds_read_b128 v[178:181], v229 offset:39936
	global_load_lds_dwordx4 v[236:237], off
	v_lshl_add_u64 v[234:235], v[234:235], 0, v[196:197]
	s_mov_b32 m0, s15
	s_nop 0
	global_load_lds_dwordx4 v[234:235], off
	s_waitcnt vmcnt(8) lgkmcnt(0)
	s_barrier
	v_mfma_f32_16x16x32_bf16 v[126:129], v[146:149], v[174:177], v[126:129]
	v_mfma_f32_16x16x32_bf16 v[122:125], v[154:157], v[174:177], v[122:125]
	v_mfma_f32_16x16x32_bf16 v[110:113], v[146:149], v[170:173], v[110:113]
	v_mfma_f32_16x16x32_bf16 v[106:109], v[154:157], v[170:173], v[106:109]
	v_mfma_f32_16x16x32_bf16 v[94:97], v[146:149], v[166:169], v[94:97]
	v_mfma_f32_16x16x32_bf16 v[90:93], v[154:157], v[166:169], v[90:93]
	v_mfma_f32_16x16x32_bf16 v[78:81], v[146:149], v[162:165], v[78:81]
	v_mfma_f32_16x16x32_bf16 v[74:77], v[154:157], v[162:165], v[74:77]
	v_mfma_f32_16x16x32_bf16 v[126:129], v[150:153], v[190:193], v[126:129]
	v_mfma_f32_16x16x32_bf16 v[122:125], v[158:161], v[190:193], v[122:125]
	v_mfma_f32_16x16x32_bf16 v[110:113], v[150:153], v[186:189], v[110:113]
	v_mfma_f32_16x16x32_bf16 v[106:109], v[158:161], v[186:189], v[106:109]
	v_mfma_f32_16x16x32_bf16 v[94:97], v[150:153], v[182:185], v[94:97]
	v_mfma_f32_16x16x32_bf16 v[90:93], v[158:161], v[182:185], v[90:93]
	v_mfma_f32_16x16x32_bf16 v[78:81], v[150:153], v[178:181], v[78:81]
	v_mfma_f32_16x16x32_bf16 v[74:77], v[158:161], v[178:181], v[74:77]
	v_mfma_f32_16x16x32_bf16 v[118:121], v[130:133], v[174:177], v[118:121]
	v_mfma_f32_16x16x32_bf16 v[114:117], v[138:141], v[174:177], v[114:117]
	v_mfma_f32_16x16x32_bf16 v[102:105], v[130:133], v[170:173], v[102:105]
	v_mfma_f32_16x16x32_bf16 v[98:101], v[138:141], v[170:173], v[98:101]
	v_mfma_f32_16x16x32_bf16 v[86:89], v[130:133], v[166:169], v[86:89]
	v_mfma_f32_16x16x32_bf16 v[82:85], v[138:141], v[166:169], v[82:85]
	v_mfma_f32_16x16x32_bf16 v[70:73], v[130:133], v[162:165], v[70:73]
	v_mfma_f32_16x16x32_bf16 v[66:69], v[138:141], v[162:165], v[66:69]
	v_mfma_f32_16x16x32_bf16 v[118:121], v[134:137], v[190:193], v[118:121]
	v_mfma_f32_16x16x32_bf16 v[114:117], v[142:145], v[190:193], v[114:117]
	v_mfma_f32_16x16x32_bf16 v[102:105], v[134:137], v[186:189], v[102:105]
	v_mfma_f32_16x16x32_bf16 v[98:101], v[142:145], v[186:189], v[98:101]
	v_mfma_f32_16x16x32_bf16 v[86:89], v[134:137], v[182:185], v[86:89]
	v_mfma_f32_16x16x32_bf16 v[82:85], v[142:145], v[182:185], v[82:85]
	v_mfma_f32_16x16x32_bf16 v[70:73], v[134:137], v[178:181], v[70:73]
	v_mfma_f32_16x16x32_bf16 v[66:69], v[142:145], v[178:181], v[66:69]
	s_barrier
	s_and_b64 vcc, exec, s[42:43]
	s_cbranch_vccnz .LBB0_565
	ds_read_b128 v[174:177], v229 offset:49152
	ds_read_b128 v[190:193], v229 offset:50176
	ds_read_b128 v[170:173], v229 offset:51200
	ds_read_b128 v[186:189], v229 offset:52224
	ds_read_b128 v[166:169], v229 offset:53248
	ds_read_b128 v[182:185], v229 offset:54272
	ds_read_b128 v[162:165], v229 offset:55296
	ds_read_b128 v[178:181], v229 offset:56320
.LBB0_565:
	s_add_u32 s68, s60, 0x40000
	s_addc_u32 s69, s61, 0
	s_add_u32 s62, s62, 0x220000
	s_addc_u32 s63, s63, 0
	s_mov_b32 m0, s17
	s_add_u32 s60, s60, 0x44000
	global_load_lds_dwordx4 v194, s[68:69]
	s_mov_b32 m0, s54
	s_addc_u32 s61, s61, 0
	global_load_lds_dwordx4 v196, s[68:69]
	s_mov_b32 m0, s70
	s_and_b64 vcc, exec, s[42:43]
	global_load_lds_dwordx4 v194, s[60:61]
	s_mov_b32 m0, s71
	s_nop 0
	global_load_lds_dwordx4 v196, s[60:61]
	s_waitcnt vmcnt(6) lgkmcnt(0)
	s_barrier
	s_cbranch_vccnz .LBB0_558
	s_waitcnt lgkmcnt(0)
	v_mfma_f32_16x16x32_bf16 v[62:65], v[146:149], v[174:177], v[62:65]
	v_mfma_f32_16x16x32_bf16 v[58:61], v[154:157], v[174:177], v[58:61]
	v_mfma_f32_16x16x32_bf16 v[46:49], v[146:149], v[170:173], v[46:49]
	v_mfma_f32_16x16x32_bf16 v[42:45], v[154:157], v[170:173], v[42:45]
	v_mfma_f32_16x16x32_bf16 v[30:33], v[146:149], v[166:169], v[30:33]
	v_mfma_f32_16x16x32_bf16 v[26:29], v[154:157], v[166:169], v[26:29]
	v_mfma_f32_16x16x32_bf16 v[14:17], v[146:149], v[162:165], v[14:17]
	v_mfma_f32_16x16x32_bf16 v[10:13], v[154:157], v[162:165], v[10:13]
	v_mfma_f32_16x16x32_bf16 v[62:65], v[150:153], v[190:193], v[62:65]
	v_mfma_f32_16x16x32_bf16 v[58:61], v[158:161], v[190:193], v[58:61]
	v_mfma_f32_16x16x32_bf16 v[46:49], v[150:153], v[186:189], v[46:49]
	v_mfma_f32_16x16x32_bf16 v[42:45], v[158:161], v[186:189], v[42:45]
	v_mfma_f32_16x16x32_bf16 v[30:33], v[150:153], v[182:185], v[30:33]
	v_mfma_f32_16x16x32_bf16 v[26:29], v[158:161], v[182:185], v[26:29]
	v_mfma_f32_16x16x32_bf16 v[14:17], v[150:153], v[178:181], v[14:17]
	v_mfma_f32_16x16x32_bf16 v[10:13], v[158:161], v[178:181], v[10:13]
	v_mfma_f32_16x16x32_bf16 v[54:57], v[130:133], v[174:177], v[54:57]
	v_mfma_f32_16x16x32_bf16 v[50:53], v[138:141], v[174:177], v[50:53]
	v_mfma_f32_16x16x32_bf16 v[38:41], v[130:133], v[170:173], v[38:41]
	v_mfma_f32_16x16x32_bf16 v[34:37], v[138:141], v[170:173], v[34:37]
	v_mfma_f32_16x16x32_bf16 v[22:25], v[130:133], v[166:169], v[22:25]
	v_mfma_f32_16x16x32_bf16 v[18:21], v[138:141], v[166:169], v[18:21]
	v_mfma_f32_16x16x32_bf16 v[6:9], v[130:133], v[162:165], v[6:9]
	v_mfma_f32_16x16x32_bf16 v[2:5], v[138:141], v[162:165], v[2:5]
	v_mfma_f32_16x16x32_bf16 v[54:57], v[134:137], v[190:193], v[54:57]
	v_mfma_f32_16x16x32_bf16 v[50:53], v[142:145], v[190:193], v[50:53]
	v_mfma_f32_16x16x32_bf16 v[38:41], v[134:137], v[186:189], v[38:41]
	v_mfma_f32_16x16x32_bf16 v[34:37], v[142:145], v[186:189], v[34:37]
	v_mfma_f32_16x16x32_bf16 v[22:25], v[134:137], v[182:185], v[22:25]
	v_mfma_f32_16x16x32_bf16 v[18:21], v[142:145], v[182:185], v[18:21]
	v_mfma_f32_16x16x32_bf16 v[6:9], v[134:137], v[178:181], v[6:9]
	v_mfma_f32_16x16x32_bf16 v[2:5], v[142:145], v[178:181], v[2:5]
	s_branch .LBB0_558

.LBB0_761:
	ds_read_b128 v[130:133], v237
	ds_read_b128 v[134:137], v237 offset:1024
	ds_read_b128 v[138:141], v237 offset:2048
	ds_read_b128 v[142:145], v237 offset:3072
	ds_read_b128 v[146:149], v238
	ds_read_b128 v[150:153], v238 offset:1024
	ds_read_b128 v[154:157], v238 offset:2048
	ds_read_b128 v[158:161], v238 offset:3072
	s_add_u32 s48, s0, 0x21c000
	s_addc_u32 s49, s1, 0
	s_cmp_eq_u32 s67, 28
	s_cselect_b32 s42, s55, s62
	s_cselect_b32 s43, s29, s63
	s_cselect_b32 s52, s45, s48
	s_cselect_b32 s53, s31, s49
	s_add_u32 s50, s42, 0xe0000
	s_addc_u32 s51, s43, 0
	s_add_u32 s48, s52, 0x220000
	s_addc_u32 s49, s53, 0
	v_lshl_add_u64 v[208:209], s[0:1], 0, v[202:203]
	s_add_i32 m0, s9, 0xc000
	ds_read_b128 v[162:165], v239
	ds_read_b128 v[166:169], v239 offset:1024
	ds_read_b128 v[170:173], v239 offset:2048
	ds_read_b128 v[174:177], v239 offset:3072
	ds_read_b128 v[178:181], v239 offset:4096
	ds_read_b128 v[182:185], v239 offset:5120
	ds_read_b128 v[186:189], v239 offset:6144
	ds_read_b128 v[190:193], v239 offset:7168
	global_load_lds_dwordx4 v[208:209], off
	v_lshl_add_u64 v[208:209], s[0:1], 0, v[200:201]
	s_add_i32 m0, s9, 0xe000
	s_nop 0
	global_load_lds_dwordx4 v[208:209], off
	s_waitcnt vmcnt(8) lgkmcnt(0)
	s_barrier
	v_mfma_f32_16x16x32_bf16 v[126:129], v[130:133], v[162:165], v[126:129]
	v_mfma_f32_16x16x32_bf16 v[122:125], v[138:141], v[162:165], v[122:125]
	v_mfma_f32_16x16x32_bf16 v[118:121], v[130:133], v[170:173], v[118:121]
	v_mfma_f32_16x16x32_bf16 v[114:117], v[138:141], v[170:173], v[114:117]
	v_mfma_f32_16x16x32_bf16 v[110:113], v[130:133], v[178:181], v[110:113]
	v_mfma_f32_16x16x32_bf16 v[106:109], v[138:141], v[178:181], v[106:109]
	v_mfma_f32_16x16x32_bf16 v[102:105], v[130:133], v[186:189], v[102:105]
	v_mfma_f32_16x16x32_bf16 v[98:101], v[138:141], v[186:189], v[98:101]
	v_mfma_f32_16x16x32_bf16 v[126:129], v[134:137], v[166:169], v[126:129]
	v_mfma_f32_16x16x32_bf16 v[122:125], v[142:145], v[166:169], v[122:125]
	v_mfma_f32_16x16x32_bf16 v[118:121], v[134:137], v[174:177], v[118:121]
	v_mfma_f32_16x16x32_bf16 v[114:117], v[142:145], v[174:177], v[114:117]
	v_mfma_f32_16x16x32_bf16 v[110:113], v[134:137], v[182:185], v[110:113]
	v_mfma_f32_16x16x32_bf16 v[106:109], v[142:145], v[182:185], v[106:109]
	v_mfma_f32_16x16x32_bf16 v[102:105], v[134:137], v[190:193], v[102:105]
	v_mfma_f32_16x16x32_bf16 v[98:101], v[142:145], v[190:193], v[98:101]
	v_mfma_f32_16x16x32_bf16 v[62:65], v[146:149], v[162:165], v[62:65]
	s_add_u32 s60, s52, 0x4000
	s_addc_u32 s61, s53, 0
	v_mfma_f32_16x16x32_bf16 v[58:61], v[154:157], v[162:165], v[58:61]
	v_mfma_f32_16x16x32_bf16 v[54:57], v[146:149], v[170:173], v[54:57]
	v_mfma_f32_16x16x32_bf16 v[50:53], v[154:157], v[170:173], v[50:53]
	v_mfma_f32_16x16x32_bf16 v[46:49], v[146:149], v[178:181], v[46:49]
	v_mfma_f32_16x16x32_bf16 v[42:45], v[154:157], v[178:181], v[42:45]
	v_mfma_f32_16x16x32_bf16 v[38:41], v[146:149], v[186:189], v[38:41]
	v_mfma_f32_16x16x32_bf16 v[34:37], v[154:157], v[186:189], v[34:37]
	v_mfma_f32_16x16x32_bf16 v[62:65], v[150:153], v[166:169], v[62:65]
	v_mfma_f32_16x16x32_bf16 v[58:61], v[158:161], v[166:169], v[58:61]
	v_mfma_f32_16x16x32_bf16 v[54:57], v[150:153], v[174:177], v[54:57]
	v_mfma_f32_16x16x32_bf16 v[50:53], v[158:161], v[174:177], v[50:53]
	v_mfma_f32_16x16x32_bf16 v[46:49], v[150:153], v[182:185], v[46:49]
	v_mfma_f32_16x16x32_bf16 v[42:45], v[158:161], v[182:185], v[42:45]
	v_mfma_f32_16x16x32_bf16 v[38:41], v[150:153], v[190:193], v[38:41]
	v_mfma_f32_16x16x32_bf16 v[34:37], v[158:161], v[190:193], v[34:37]
	s_barrier
	s_add_i32 s68, s16, s8
	s_mov_b32 m0, s68
	ds_read_b128 v[162:165], v239 offset:16384
	ds_read_b128 v[166:169], v239 offset:17408
	ds_read_b128 v[170:173], v239 offset:18432
	ds_read_b128 v[174:177], v239 offset:19456
	ds_read_b128 v[178:181], v239 offset:20480
	ds_read_b128 v[182:185], v239 offset:21504
	ds_read_b128 v[186:189], v239 offset:22528
	ds_read_b128 v[190:193], v239 offset:23552
	global_load_lds_dwordx4 v194, s[42:43]
	s_add_i32 m0, s68, 0x2000
	s_add_u32 s68, s42, 0x4000
	s_addc_u32 s69, s43, 0
	s_add_i32 s70, s17, s8
	global_load_lds_dwordx4 v196, s[42:43]
	s_mov_b32 m0, s70
	s_nop 0
	global_load_lds_dwordx4 v194, s[68:69]
	s_add_i32 m0, s70, 0x2000
	s_nop 0
	global_load_lds_dwordx4 v196, s[68:69]
	s_waitcnt vmcnt(6) lgkmcnt(0)
	s_barrier
	v_mfma_f32_16x16x32_bf16 v[94:97], v[130:133], v[162:165], v[94:97]
	v_mfma_f32_16x16x32_bf16 v[90:93], v[138:141], v[162:165], v[90:93]
	v_mfma_f32_16x16x32_bf16 v[86:89], v[130:133], v[170:173], v[86:89]
	v_mfma_f32_16x16x32_bf16 v[82:85], v[138:141], v[170:173], v[82:85]
	v_mfma_f32_16x16x32_bf16 v[78:81], v[130:133], v[178:181], v[78:81]
	v_mfma_f32_16x16x32_bf16 v[74:77], v[138:141], v[178:181], v[74:77]
	v_mfma_f32_16x16x32_bf16 v[70:73], v[130:133], v[186:189], v[70:73]
	v_mfma_f32_16x16x32_bf16 v[66:69], v[138:141], v[186:189], v[66:69]
	v_mfma_f32_16x16x32_bf16 v[94:97], v[134:137], v[166:169], v[94:97]
	v_mfma_f32_16x16x32_bf16 v[90:93], v[142:145], v[166:169], v[90:93]
	v_mfma_f32_16x16x32_bf16 v[86:89], v[134:137], v[174:177], v[86:89]
	v_mfma_f32_16x16x32_bf16 v[82:85], v[142:145], v[174:177], v[82:85]
	v_mfma_f32_16x16x32_bf16 v[78:81], v[134:137], v[182:185], v[78:81]
	v_mfma_f32_16x16x32_bf16 v[74:77], v[142:145], v[182:185], v[74:77]
	v_mfma_f32_16x16x32_bf16 v[70:73], v[134:137], v[190:193], v[70:73]
	v_mfma_f32_16x16x32_bf16 v[66:69], v[142:145], v[190:193], v[66:69]
	v_mfma_f32_16x16x32_bf16 v[30:33], v[146:149], v[162:165], v[30:33]
	v_mfma_f32_16x16x32_bf16 v[26:29], v[154:157], v[162:165], v[26:29]
	v_mfma_f32_16x16x32_bf16 v[22:25], v[146:149], v[170:173], v[22:25]
	v_mfma_f32_16x16x32_bf16 v[18:21], v[154:157], v[170:173], v[18:21]
	v_mfma_f32_16x16x32_bf16 v[14:17], v[146:149], v[178:181], v[14:17]
	v_mfma_f32_16x16x32_bf16 v[10:13], v[154:157], v[178:181], v[10:13]
	v_mfma_f32_16x16x32_bf16 v[6:9], v[146:149], v[186:189], v[6:9]
	v_mfma_f32_16x16x32_bf16 v[2:5], v[154:157], v[186:189], v[2:5]
	v_mfma_f32_16x16x32_bf16 v[30:33], v[150:153], v[166:169], v[30:33]
	v_mfma_f32_16x16x32_bf16 v[26:29], v[158:161], v[166:169], v[26:29]
	v_mfma_f32_16x16x32_bf16 v[22:25], v[150:153], v[174:177], v[22:25]
	v_mfma_f32_16x16x32_bf16 v[18:21], v[158:161], v[174:177], v[18:21]
	v_mfma_f32_16x16x32_bf16 v[14:17], v[150:153], v[182:185], v[14:17]
	v_mfma_f32_16x16x32_bf16 v[10:13], v[158:161], v[182:185], v[10:13]
	v_mfma_f32_16x16x32_bf16 v[6:9], v[150:153], v[190:193], v[6:9]
	v_mfma_f32_16x16x32_bf16 v[2:5], v[158:161], v[190:193], v[2:5]
	s_mov_b32 m0, s9
	s_nop 0
	global_load_lds_dwordx4 v194, s[52:53]
	s_mov_b32 m0, s10
	s_nop 0
	global_load_lds_dwordx4 v196, s[52:53]
	s_barrier
	s_add_i32 s52, 0, 0x18000
	s_add_i32 s53, 0, 0x1c000
	v_add_u32_e32 v142, s52, v228
	v_add_u32_e32 v158, s53, v228
	ds_read_b128 v[130:133], v142
	ds_read_b128 v[134:137], v142 offset:1024
	ds_read_b128 v[138:141], v142 offset:2048
	ds_read_b128 v[142:145], v142 offset:3072
	ds_read_b128 v[146:149], v158
	ds_read_b128 v[150:153], v158 offset:1024
	ds_read_b128 v[154:157], v158 offset:2048
	ds_read_b128 v[158:161], v158 offset:3072
	s_mov_b32 m0, s11
	ds_read_b128 v[162:165], v239 offset:32768
	ds_read_b128 v[166:169], v239 offset:33792
	ds_read_b128 v[170:173], v239 offset:34816
	ds_read_b128 v[174:177], v239 offset:35840
	ds_read_b128 v[178:181], v239 offset:36864
	ds_read_b128 v[182:185], v239 offset:37888
	ds_read_b128 v[186:189], v239 offset:38912
	ds_read_b128 v[190:193], v239 offset:39936
	global_load_lds_dwordx4 v194, s[60:61]
	s_mov_b32 m0, s12
	s_nop 0
	global_load_lds_dwordx4 v196, s[60:61]
	s_waitcnt vmcnt(8) lgkmcnt(0)
	s_barrier
	v_mfma_f32_16x16x32_bf16 v[126:129], v[130:133], v[162:165], v[126:129]
	v_mfma_f32_16x16x32_bf16 v[122:125], v[138:141], v[162:165], v[122:125]
	v_mfma_f32_16x16x32_bf16 v[118:121], v[130:133], v[170:173], v[118:121]
	v_mfma_f32_16x16x32_bf16 v[114:117], v[138:141], v[170:173], v[114:117]
	v_mfma_f32_16x16x32_bf16 v[110:113], v[130:133], v[178:181], v[110:113]
	v_mfma_f32_16x16x32_bf16 v[106:109], v[138:141], v[178:181], v[106:109]
	v_mfma_f32_16x16x32_bf16 v[102:105], v[130:133], v[186:189], v[102:105]
	v_mfma_f32_16x16x32_bf16 v[98:101], v[138:141], v[186:189], v[98:101]
	v_mfma_f32_16x16x32_bf16 v[126:129], v[134:137], v[166:169], v[126:129]
	v_mfma_f32_16x16x32_bf16 v[122:125], v[142:145], v[166:169], v[122:125]
	v_mfma_f32_16x16x32_bf16 v[118:121], v[134:137], v[174:177], v[118:121]
	v_mfma_f32_16x16x32_bf16 v[114:117], v[142:145], v[174:177], v[114:117]
	v_mfma_f32_16x16x32_bf16 v[110:113], v[134:137], v[182:185], v[110:113]
	v_mfma_f32_16x16x32_bf16 v[106:109], v[142:145], v[182:185], v[106:109]
	v_mfma_f32_16x16x32_bf16 v[102:105], v[134:137], v[190:193], v[102:105]
	v_mfma_f32_16x16x32_bf16 v[98:101], v[142:145], v[190:193], v[98:101]
	v_mfma_f32_16x16x32_bf16 v[62:65], v[146:149], v[162:165], v[62:65]
	v_mfma_f32_16x16x32_bf16 v[58:61], v[154:157], v[162:165], v[58:61]
	v_mfma_f32_16x16x32_bf16 v[54:57], v[146:149], v[170:173], v[54:57]
	v_mfma_f32_16x16x32_bf16 v[50:53], v[154:157], v[170:173], v[50:53]
	v_mfma_f32_16x16x32_bf16 v[46:49], v[146:149], v[178:181], v[46:49]
	v_mfma_f32_16x16x32_bf16 v[42:45], v[154:157], v[178:181], v[42:45]
	v_mfma_f32_16x16x32_bf16 v[38:41], v[146:149], v[186:189], v[38:41]
	v_mfma_f32_16x16x32_bf16 v[34:37], v[154:157], v[186:189], v[34:37]
	v_mfma_f32_16x16x32_bf16 v[62:65], v[150:153], v[166:169], v[62:65]
	v_mfma_f32_16x16x32_bf16 v[58:61], v[158:161], v[166:169], v[58:61]
	v_mfma_f32_16x16x32_bf16 v[54:57], v[150:153], v[174:177], v[54:57]
	v_mfma_f32_16x16x32_bf16 v[50:53], v[158:161], v[174:177], v[50:53]
	v_mfma_f32_16x16x32_bf16 v[46:49], v[150:153], v[182:185], v[46:49]
	v_mfma_f32_16x16x32_bf16 v[42:45], v[158:161], v[182:185], v[42:45]
	v_mfma_f32_16x16x32_bf16 v[38:41], v[150:153], v[190:193], v[38:41]
	v_mfma_f32_16x16x32_bf16 v[34:37], v[158:161], v[190:193], v[34:37]
	s_barrier
	s_add_i32 s52, s52, s8
	s_mov_b32 m0, s52
	ds_read_b128 v[162:165], v239 offset:49152
	ds_read_b128 v[166:169], v239 offset:50176
	ds_read_b128 v[170:173], v239 offset:51200
	ds_read_b128 v[174:177], v239 offset:52224
	ds_read_b128 v[178:181], v239 offset:53248
	ds_read_b128 v[182:185], v239 offset:54272
	ds_read_b128 v[186:189], v239 offset:55296
	ds_read_b128 v[190:193], v239 offset:56320
	global_load_lds_dwordx4 v194, s[50:51]
	s_add_i32 m0, s52, 0x2000
	s_add_u32 s42, s42, 0xe4000
	v_lshl_add_u64 v[208:209], s[50:51], 0, v[196:197]
	s_addc_u32 s43, s43, 0
	s_add_i32 s50, s53, s8
	global_load_lds_dwordx4 v[208:209], off
	s_mov_b32 m0, s50
	s_nop 0
	global_load_lds_dwordx4 v194, s[42:43]
	s_add_i32 m0, s50, 0x2000
	s_nop 0
	global_load_lds_dwordx4 v196, s[42:43]
	s_waitcnt vmcnt(6) lgkmcnt(0)
	s_barrier
	v_mfma_f32_16x16x32_bf16 v[94:97], v[130:133], v[162:165], v[94:97]
	v_mfma_f32_16x16x32_bf16 v[90:93], v[138:141], v[162:165], v[90:93]
	v_mfma_f32_16x16x32_bf16 v[86:89], v[130:133], v[170:173], v[86:89]
	v_mfma_f32_16x16x32_bf16 v[82:85], v[138:141], v[170:173], v[82:85]
	v_mfma_f32_16x16x32_bf16 v[78:81], v[130:133], v[178:181], v[78:81]
	v_mfma_f32_16x16x32_bf16 v[74:77], v[138:141], v[178:181], v[74:77]
	v_mfma_f32_16x16x32_bf16 v[70:73], v[130:133], v[186:189], v[70:73]
	v_mfma_f32_16x16x32_bf16 v[66:69], v[138:141], v[186:189], v[66:69]
	v_mfma_f32_16x16x32_bf16 v[94:97], v[134:137], v[166:169], v[94:97]
	v_mfma_f32_16x16x32_bf16 v[90:93], v[142:145], v[166:169], v[90:93]
	v_mfma_f32_16x16x32_bf16 v[86:89], v[134:137], v[174:177], v[86:89]
	v_mfma_f32_16x16x32_bf16 v[82:85], v[142:145], v[174:177], v[82:85]
	v_mfma_f32_16x16x32_bf16 v[78:81], v[134:137], v[182:185], v[78:81]
	v_mfma_f32_16x16x32_bf16 v[74:77], v[142:145], v[182:185], v[74:77]
	v_mfma_f32_16x16x32_bf16 v[70:73], v[134:137], v[190:193], v[70:73]
	v_mfma_f32_16x16x32_bf16 v[66:69], v[142:145], v[190:193], v[66:69]
	v_mfma_f32_16x16x32_bf16 v[30:33], v[146:149], v[162:165], v[30:33]
	v_mfma_f32_16x16x32_bf16 v[26:29], v[154:157], v[162:165], v[26:29]
	v_mfma_f32_16x16x32_bf16 v[22:25], v[146:149], v[170:173], v[22:25]
	v_mfma_f32_16x16x32_bf16 v[18:21], v[154:157], v[170:173], v[18:21]
	v_mfma_f32_16x16x32_bf16 v[14:17], v[146:149], v[178:181], v[14:17]
	v_mfma_f32_16x16x32_bf16 v[10:13], v[154:157], v[178:181], v[10:13]
	v_mfma_f32_16x16x32_bf16 v[6:9], v[146:149], v[186:189], v[6:9]
	v_mfma_f32_16x16x32_bf16 v[2:5], v[154:157], v[186:189], v[2:5]
	v_mfma_f32_16x16x32_bf16 v[30:33], v[150:153], v[166:169], v[30:33]
	v_mfma_f32_16x16x32_bf16 v[26:29], v[158:161], v[166:169], v[26:29]
	v_mfma_f32_16x16x32_bf16 v[22:25], v[150:153], v[174:177], v[22:25]
	v_mfma_f32_16x16x32_bf16 v[18:21], v[158:161], v[174:177], v[18:21]
	v_mfma_f32_16x16x32_bf16 v[14:17], v[150:153], v[182:185], v[14:17]
	v_mfma_f32_16x16x32_bf16 v[10:13], v[158:161], v[182:185], v[10:13]
	v_mfma_f32_16x16x32_bf16 v[6:9], v[150:153], v[190:193], v[6:9]
	v_mfma_f32_16x16x32_bf16 v[2:5], v[158:161], v[190:193], v[2:5]
	s_mov_b32 m0, s14
	s_nop 0
	global_load_lds_dwordx4 v194, s[48:49]
	s_mov_b32 m0, s15
	s_nop 0
	global_load_lds_dwordx4 v196, s[48:49]
	s_barrier
	s_add_i32 s67, s67, 2
	s_add_u32 s62, s62, 0x1c0000
	s_addc_u32 s63, s63, 0
	s_add_u32 s0, s0, 0x440000
	s_addc_u32 s1, s1, 0
	s_cmp_gt_u32 s67, 29
	s_cbranch_scc0 .LBB0_761
	s_and_b64 vcc, exec, s[26:27]
	s_cbranch_vccz .LBB0_764
	s_barrier

.LBB0_902:
	s_mov_b32 m0, s23
	s_nop 0
	global_load_lds_dwordx4 v194, s[70:71]
	s_mov_b32 m0, s31
	s_nop 0
	global_load_lds_dwordx4 v196, s[70:71]
	s_barrier
	s_add_i32 s78, s78, 2
	s_add_u32 s76, s76, 0x1c0000
	s_addc_u32 s77, s77, 0
	s_add_u32 s62, s62, 0x440000
	s_addc_u32 s63, s63, 0
	s_cmp_gt_u32 s78, 29
	s_cbranch_scc1 .LBB0_911
.LBB0_903:
	ds_read_b128 v[146:149], v225
	ds_read_b128 v[150:153], v225 offset:1024
	ds_read_b128 v[154:157], v225 offset:2048
	ds_read_b128 v[158:161], v225 offset:3072
	ds_read_b128 v[130:133], v227
	ds_read_b128 v[134:137], v227 offset:1024
	ds_read_b128 v[138:141], v227 offset:2048
	ds_read_b128 v[142:145], v227 offset:3072
	v_lshl_add_u64 v[234:235], v[210:211], 0, s[62:63]
	s_add_i32 m0, s8, 0xc000
	s_waitcnt lgkmcnt(0)
	ds_read_b128 v[174:177], v228
	ds_read_b128 v[190:193], v228 offset:1024
	ds_read_b128 v[170:173], v228 offset:2048
	ds_read_b128 v[186:189], v228 offset:3072
	ds_read_b128 v[166:169], v228 offset:4096
	ds_read_b128 v[182:185], v228 offset:5120
	ds_read_b128 v[162:165], v228 offset:6144
	ds_read_b128 v[178:181], v228 offset:7168
	global_load_lds_dwordx4 v[234:235], off
	v_lshl_add_u64 v[234:235], v[212:213], 0, s[62:63]
	s_add_i32 m0, s8, 0xe000
	s_nop 0
	global_load_lds_dwordx4 v[234:235], off
	s_waitcnt vmcnt(8) lgkmcnt(0)
	s_barrier
	v_mfma_f32_16x16x32_bf16 v[126:129], v[146:149], v[174:177], v[126:129]
	v_mfma_f32_16x16x32_bf16 v[122:125], v[154:157], v[174:177], v[122:125]
	v_mfma_f32_16x16x32_bf16 v[118:121], v[146:149], v[170:173], v[118:121]
	v_mfma_f32_16x16x32_bf16 v[114:117], v[154:157], v[170:173], v[114:117]
	v_mfma_f32_16x16x32_bf16 v[110:113], v[146:149], v[166:169], v[110:113]
	v_mfma_f32_16x16x32_bf16 v[106:109], v[154:157], v[166:169], v[106:109]
	v_mfma_f32_16x16x32_bf16 v[102:105], v[146:149], v[162:165], v[102:105]
	v_mfma_f32_16x16x32_bf16 v[98:101], v[154:157], v[162:165], v[98:101]
	v_mfma_f32_16x16x32_bf16 v[126:129], v[150:153], v[190:193], v[126:129]
	v_mfma_f32_16x16x32_bf16 v[122:125], v[158:161], v[190:193], v[122:125]
	v_mfma_f32_16x16x32_bf16 v[118:121], v[150:153], v[186:189], v[118:121]
	v_mfma_f32_16x16x32_bf16 v[114:117], v[158:161], v[186:189], v[114:117]
	v_mfma_f32_16x16x32_bf16 v[110:113], v[150:153], v[182:185], v[110:113]
	v_mfma_f32_16x16x32_bf16 v[106:109], v[158:161], v[182:185], v[106:109]
	v_mfma_f32_16x16x32_bf16 v[102:105], v[150:153], v[178:181], v[102:105]
	v_mfma_f32_16x16x32_bf16 v[98:101], v[158:161], v[178:181], v[98:101]
	v_mfma_f32_16x16x32_bf16 v[94:97], v[130:133], v[174:177], v[94:97]
	v_mfma_f32_16x16x32_bf16 v[90:93], v[138:141], v[174:177], v[90:93]
	v_mfma_f32_16x16x32_bf16 v[86:89], v[130:133], v[170:173], v[86:89]
	v_mfma_f32_16x16x32_bf16 v[82:85], v[138:141], v[170:173], v[82:85]
	v_mfma_f32_16x16x32_bf16 v[78:81], v[130:133], v[166:169], v[78:81]
	v_mfma_f32_16x16x32_bf16 v[74:77], v[138:141], v[166:169], v[74:77]
	v_mfma_f32_16x16x32_bf16 v[70:73], v[130:133], v[162:165], v[70:73]
	v_mfma_f32_16x16x32_bf16 v[66:69], v[138:141], v[162:165], v[66:69]
	v_mfma_f32_16x16x32_bf16 v[94:97], v[134:137], v[190:193], v[94:97]
	v_mfma_f32_16x16x32_bf16 v[90:93], v[142:145], v[190:193], v[90:93]
	v_mfma_f32_16x16x32_bf16 v[86:89], v[134:137], v[186:189], v[86:89]
	v_mfma_f32_16x16x32_bf16 v[82:85], v[142:145], v[186:189], v[82:85]
	v_mfma_f32_16x16x32_bf16 v[78:81], v[134:137], v[182:185], v[78:81]
	v_mfma_f32_16x16x32_bf16 v[74:77], v[142:145], v[182:185], v[74:77]
	v_mfma_f32_16x16x32_bf16 v[70:73], v[134:137], v[178:181], v[70:73]
	v_mfma_f32_16x16x32_bf16 v[66:69], v[142:145], v[178:181], v[66:69]
	s_barrier
	v_cmp_ne_u32_e64 s[42:43], 1, v233
	s_andn2_b64 vcc, exec, s[44:45]
	s_cbranch_vccnz .LBB0_905
	ds_read_b128 v[174:177], v228 offset:16384
	ds_read_b128 v[190:193], v228 offset:17408
	ds_read_b128 v[170:173], v228 offset:18432
	ds_read_b128 v[186:189], v228 offset:19456
	ds_read_b128 v[166:169], v228 offset:20480
	ds_read_b128 v[182:185], v228 offset:21504
	ds_read_b128 v[162:165], v228 offset:22528
	ds_read_b128 v[178:181], v228 offset:23552
.LBB0_905:
	s_add_u32 s68, s0, s62
	s_addc_u32 s69, s1, s63
	s_add_u32 s70, s68, 0x440000
	s_addc_u32 s71, s69, 0
	s_cmp_eq_u32 s62, 0x3fc0000
	s_cselect_b64 s[72:73], -1, 0
	s_and_b64 s[68:69], s[72:73], exec
	s_cselect_b32 s69, s37, s77
	s_cselect_b32 s68, s75, s76
	s_mov_b32 m0, s9
	s_cselect_b32 s71, s35, s71
	s_cselect_b32 s70, s74, s70
	s_add_u32 s80, s68, 0x4000
	global_load_lds_dwordx4 v194, s[68:69]
	s_mov_b32 m0, s10
	s_addc_u32 s81, s69, 0
	global_load_lds_dwordx4 v196, s[68:69]
	s_mov_b32 m0, s11
	s_and_b64 vcc, exec, s[42:43]
	global_load_lds_dwordx4 v194, s[80:81]
	s_mov_b32 m0, s12
	s_nop 0
	global_load_lds_dwordx4 v196, s[80:81]
	s_waitcnt vmcnt(6) lgkmcnt(0)
	s_barrier
	s_cbranch_vccnz .LBB0_907
	s_waitcnt lgkmcnt(0)
	v_mfma_f32_16x16x32_bf16 v[62:65], v[146:149], v[174:177], v[62:65]
	v_mfma_f32_16x16x32_bf16 v[58:61], v[154:157], v[174:177], v[58:61]
	v_mfma_f32_16x16x32_bf16 v[54:57], v[146:149], v[170:173], v[54:57]
	v_mfma_f32_16x16x32_bf16 v[50:53], v[154:157], v[170:173], v[50:53]
	v_mfma_f32_16x16x32_bf16 v[46:49], v[146:149], v[166:169], v[46:49]
	v_mfma_f32_16x16x32_bf16 v[42:45], v[154:157], v[166:169], v[42:45]
	v_mfma_f32_16x16x32_bf16 v[38:41], v[146:149], v[162:165], v[38:41]
	v_mfma_f32_16x16x32_bf16 v[34:37], v[154:157], v[162:165], v[34:37]
	v_mfma_f32_16x16x32_bf16 v[62:65], v[150:153], v[190:193], v[62:65]
	v_mfma_f32_16x16x32_bf16 v[58:61], v[158:161], v[190:193], v[58:61]
	v_mfma_f32_16x16x32_bf16 v[54:57], v[150:153], v[186:189], v[54:57]
	v_mfma_f32_16x16x32_bf16 v[50:53], v[158:161], v[186:189], v[50:53]
	v_mfma_f32_16x16x32_bf16 v[46:49], v[150:153], v[182:185], v[46:49]
	v_mfma_f32_16x16x32_bf16 v[42:45], v[158:161], v[182:185], v[42:45]
	v_mfma_f32_16x16x32_bf16 v[38:41], v[150:153], v[178:181], v[38:41]
	v_mfma_f32_16x16x32_bf16 v[34:37], v[158:161], v[178:181], v[34:37]
	v_mfma_f32_16x16x32_bf16 v[30:33], v[130:133], v[174:177], v[30:33]
	v_mfma_f32_16x16x32_bf16 v[26:29], v[138:141], v[174:177], v[26:29]
	v_mfma_f32_16x16x32_bf16 v[22:25], v[130:133], v[170:173], v[22:25]
	v_mfma_f32_16x16x32_bf16 v[18:21], v[138:141], v[170:173], v[18:21]
	v_mfma_f32_16x16x32_bf16 v[14:17], v[130:133], v[166:169], v[14:17]
	v_mfma_f32_16x16x32_bf16 v[10:13], v[138:141], v[166:169], v[10:13]
	v_mfma_f32_16x16x32_bf16 v[6:9], v[130:133], v[162:165], v[6:9]
	v_mfma_f32_16x16x32_bf16 v[2:5], v[138:141], v[162:165], v[2:5]
	v_mfma_f32_16x16x32_bf16 v[30:33], v[134:137], v[190:193], v[30:33]
	v_mfma_f32_16x16x32_bf16 v[26:29], v[142:145], v[190:193], v[26:29]
	v_mfma_f32_16x16x32_bf16 v[22:25], v[134:137], v[186:189], v[22:25]
	v_mfma_f32_16x16x32_bf16 v[18:21], v[142:145], v[186:189], v[18:21]
	v_mfma_f32_16x16x32_bf16 v[14:17], v[134:137], v[182:185], v[14:17]
	v_mfma_f32_16x16x32_bf16 v[10:13], v[142:145], v[182:185], v[10:13]
	v_mfma_f32_16x16x32_bf16 v[6:9], v[134:137], v[178:181], v[6:9]
	v_mfma_f32_16x16x32_bf16 v[2:5], v[142:145], v[178:181], v[2:5]
.LBB0_907:
	s_and_b64 vcc, s[40:41], s[72:73]
	v_cndmask_b32_e64 v131, v209, 0, vcc
	v_cndmask_b32_e32 v130, v208, v198, vcc
	v_lshl_add_u64 v[234:235], s[70:71], 0, v[130:131]
	s_mov_b32 m0, s8
	s_nop 0
	global_load_lds_dwordx4 v194, s[70:71]
	s_mov_b32 m0, s13
	s_nop 0
	global_load_lds_dwordx4 v196, s[70:71]
	s_barrier
	v_add_u32_e32 v130, 0x18000, v224
	v_add_u32_e32 v142, 0x1c000, v224
	ds_read_b128 v[146:149], v130
	ds_read_b128 v[150:153], v130 offset:1024
	ds_read_b128 v[154:157], v130 offset:2048
	ds_read_b128 v[158:161], v130 offset:3072
	ds_read_b128 v[130:133], v142
	ds_read_b128 v[134:137], v142 offset:1024
	ds_read_b128 v[138:141], v142 offset:2048
	ds_read_b128 v[142:145], v142 offset:3072
	s_mov_b32 m0, s14
	v_lshl_add_u64 v[236:237], v[234:235], 0, v[194:195]
	s_waitcnt lgkmcnt(0)
	ds_read_b128 v[174:177], v228 offset:32768
	ds_read_b128 v[190:193], v228 offset:33792
	ds_read_b128 v[170:173], v228 offset:34816
	ds_read_b128 v[186:189], v228 offset:35840
	ds_read_b128 v[166:169], v228 offset:36864
	ds_read_b128 v[182:185], v228 offset:37888
	ds_read_b128 v[162:165], v228 offset:38912
	ds_read_b128 v[178:181], v228 offset:39936
	global_load_lds_dwordx4 v[236:237], off
	v_lshl_add_u64 v[234:235], v[234:235], 0, v[196:197]
	s_mov_b32 m0, s15
	s_nop 0
	global_load_lds_dwordx4 v[234:235], off
	s_waitcnt vmcnt(8) lgkmcnt(0)
	s_barrier
	v_mfma_f32_16x16x32_bf16 v[126:129], v[146:149], v[174:177], v[126:129]
	v_mfma_f32_16x16x32_bf16 v[122:125], v[154:157], v[174:177], v[122:125]
	v_mfma_f32_16x16x32_bf16 v[118:121], v[146:149], v[170:173], v[118:121]
	v_mfma_f32_16x16x32_bf16 v[114:117], v[154:157], v[170:173], v[114:117]
	v_mfma_f32_16x16x32_bf16 v[110:113], v[146:149], v[166:169], v[110:113]
	v_mfma_f32_16x16x32_bf16 v[106:109], v[154:157], v[166:169], v[106:109]
	v_mfma_f32_16x16x32_bf16 v[102:105], v[146:149], v[162:165], v[102:105]
	v_mfma_f32_16x16x32_bf16 v[98:101], v[154:157], v[162:165], v[98:101]
	v_mfma_f32_16x16x32_bf16 v[126:129], v[150:153], v[190:193], v[126:129]
	v_mfma_f32_16x16x32_bf16 v[122:125], v[158:161], v[190:193], v[122:125]
	v_mfma_f32_16x16x32_bf16 v[118:121], v[150:153], v[186:189], v[118:121]
	v_mfma_f32_16x16x32_bf16 v[114:117], v[158:161], v[186:189], v[114:117]
	v_mfma_f32_16x16x32_bf16 v[110:113], v[150:153], v[182:185], v[110:113]
	v_mfma_f32_16x16x32_bf16 v[106:109], v[158:161], v[182:185], v[106:109]
	v_mfma_f32_16x16x32_bf16 v[102:105], v[150:153], v[178:181], v[102:105]
	v_mfma_f32_16x16x32_bf16 v[98:101], v[158:161], v[178:181], v[98:101]
	v_mfma_f32_16x16x32_bf16 v[94:97], v[130:133], v[174:177], v[94:97]
	v_mfma_f32_16x16x32_bf16 v[90:93], v[138:141], v[174:177], v[90:93]
	v_mfma_f32_16x16x32_bf16 v[86:89], v[130:133], v[170:173], v[86:89]
	v_mfma_f32_16x16x32_bf16 v[82:85], v[138:141], v[170:173], v[82:85]
	v_mfma_f32_16x16x32_bf16 v[78:81], v[130:133], v[166:169], v[78:81]
	v_mfma_f32_16x16x32_bf16 v[74:77], v[138:141], v[166:169], v[74:77]
	v_mfma_f32_16x16x32_bf16 v[70:73], v[130:133], v[162:165], v[70:73]
	v_mfma_f32_16x16x32_bf16 v[66:69], v[138:141], v[162:165], v[66:69]
	v_mfma_f32_16x16x32_bf16 v[94:97], v[134:137], v[190:193], v[94:97]
	v_mfma_f32_16x16x32_bf16 v[90:93], v[142:145], v[190:193], v[90:93]
	v_mfma_f32_16x16x32_bf16 v[86:89], v[134:137], v[186:189], v[86:89]
	v_mfma_f32_16x16x32_bf16 v[82:85], v[142:145], v[186:189], v[82:85]
	v_mfma_f32_16x16x32_bf16 v[78:81], v[134:137], v[182:185], v[78:81]
	v_mfma_f32_16x16x32_bf16 v[74:77], v[142:145], v[182:185], v[74:77]
	v_mfma_f32_16x16x32_bf16 v[70:73], v[134:137], v[178:181], v[70:73]
	v_mfma_f32_16x16x32_bf16 v[66:69], v[142:145], v[178:181], v[66:69]
	s_barrier
	s_and_b64 vcc, exec, s[42:43]
	s_cbranch_vccnz .LBB0_909
	ds_read_b128 v[174:177], v228 offset:49152
	ds_read_b128 v[190:193], v228 offset:50176
	ds_read_b128 v[170:173], v228 offset:51200
	ds_read_b128 v[186:189], v228 offset:52224
	ds_read_b128 v[166:169], v228 offset:53248
	ds_read_b128 v[182:185], v228 offset:54272
	ds_read_b128 v[162:165], v228 offset:55296
	ds_read_b128 v[178:181], v228 offset:56320
.LBB0_909:
	s_add_u32 s72, s68, 0xe0000
	s_addc_u32 s73, s69, 0
	s_add_u32 s70, s70, 0x220000
	s_addc_u32 s71, s71, 0
	s_mov_b32 m0, s16
	s_add_u32 s68, s68, 0xe4000
	global_load_lds_dwordx4 v194, s[72:73]
	s_mov_b32 m0, s17
	s_addc_u32 s69, s69, 0
	global_load_lds_dwordx4 v196, s[72:73]
	s_mov_b32 m0, s54
	s_and_b64 vcc, exec, s[42:43]
	global_load_lds_dwordx4 v194, s[68:69]
	s_mov_b32 m0, s55
	s_nop 0
	global_load_lds_dwordx4 v196, s[68:69]
	s_waitcnt vmcnt(6) lgkmcnt(0)
	s_barrier
	s_cbranch_vccnz .LBB0_902
	s_waitcnt lgkmcnt(0)
	v_mfma_f32_16x16x32_bf16 v[62:65], v[146:149], v[174:177], v[62:65]
	v_mfma_f32_16x16x32_bf16 v[58:61], v[154:157], v[174:177], v[58:61]
	v_mfma_f32_16x16x32_bf16 v[54:57], v[146:149], v[170:173], v[54:57]
	v_mfma_f32_16x16x32_bf16 v[50:53], v[154:157], v[170:173], v[50:53]
	v_mfma_f32_16x16x32_bf16 v[46:49], v[146:149], v[166:169], v[46:49]
	v_mfma_f32_16x16x32_bf16 v[42:45], v[154:157], v[166:169], v[42:45]
	v_mfma_f32_16x16x32_bf16 v[38:41], v[146:149], v[162:165], v[38:41]
	v_mfma_f32_16x16x32_bf16 v[34:37], v[154:157], v[162:165], v[34:37]
	v_mfma_f32_16x16x32_bf16 v[62:65], v[150:153], v[190:193], v[62:65]
	v_mfma_f32_16x16x32_bf16 v[58:61], v[158:161], v[190:193], v[58:61]
	v_mfma_f32_16x16x32_bf16 v[54:57], v[150:153], v[186:189], v[54:57]
	v_mfma_f32_16x16x32_bf16 v[50:53], v[158:161], v[186:189], v[50:53]
	v_mfma_f32_16x16x32_bf16 v[46:49], v[150:153], v[182:185], v[46:49]
	v_mfma_f32_16x16x32_bf16 v[42:45], v[158:161], v[182:185], v[42:45]
	v_mfma_f32_16x16x32_bf16 v[38:41], v[150:153], v[178:181], v[38:41]
	v_mfma_f32_16x16x32_bf16 v[34:37], v[158:161], v[178:181], v[34:37]
	v_mfma_f32_16x16x32_bf16 v[30:33], v[130:133], v[174:177], v[30:33]
	v_mfma_f32_16x16x32_bf16 v[26:29], v[138:141], v[174:177], v[26:29]
	v_mfma_f32_16x16x32_bf16 v[22:25], v[130:133], v[170:173], v[22:25]
	v_mfma_f32_16x16x32_bf16 v[18:21], v[138:141], v[170:173], v[18:21]
	v_mfma_f32_16x16x32_bf16 v[14:17], v[130:133], v[166:169], v[14:17]
	v_mfma_f32_16x16x32_bf16 v[10:13], v[138:141], v[166:169], v[10:13]
	v_mfma_f32_16x16x32_bf16 v[6:9], v[130:133], v[162:165], v[6:9]
	v_mfma_f32_16x16x32_bf16 v[2:5], v[138:141], v[162:165], v[2:5]
	v_mfma_f32_16x16x32_bf16 v[30:33], v[134:137], v[190:193], v[30:33]
	v_mfma_f32_16x16x32_bf16 v[26:29], v[142:145], v[190:193], v[26:29]
	v_mfma_f32_16x16x32_bf16 v[22:25], v[134:137], v[186:189], v[22:25]
	v_mfma_f32_16x16x32_bf16 v[18:21], v[142:145], v[186:189], v[18:21]
	v_mfma_f32_16x16x32_bf16 v[14:17], v[134:137], v[182:185], v[14:17]
	v_mfma_f32_16x16x32_bf16 v[10:13], v[142:145], v[182:185], v[10:13]
	v_mfma_f32_16x16x32_bf16 v[6:9], v[134:137], v[178:181], v[6:9]
	v_mfma_f32_16x16x32_bf16 v[2:5], v[142:145], v[178:181], v[2:5]
	s_branch .LBB0_902

.LBB0_1288:
	s_mov_b32 m0, s27
	s_nop 0
	global_load_lds_dwordx4 v194, s[56:57]
	s_mov_b32 m0, s54
	s_nop 0
	global_load_lds_dwordx4 v196, s[56:57]
	s_barrier
	s_add_i32 s67, s67, 2
	s_add_u32 s62, s62, 0x80000
	s_addc_u32 s63, s63, 0
	s_add_u32 s48, s48, 0x440000
	s_addc_u32 s49, s49, 0
	s_cmp_gt_u32 s67, 29
	s_cbranch_scc1 .LBB0_1297
.LBB0_1289:
	v_add_u32_e32 v142, 0x14000, v229
	ds_read_b128 v[146:149], v230
	ds_read_b128 v[150:153], v230 offset:1024
	ds_read_b128 v[154:157], v230 offset:2048
	ds_read_b128 v[158:161], v230 offset:3072
	ds_read_b128 v[130:133], v142
	ds_read_b128 v[134:137], v142 offset:1024
	ds_read_b128 v[138:141], v142 offset:2048
	ds_read_b128 v[142:145], v142 offset:3072
	v_lshl_add_u64 v[234:235], v[222:223], 0, s[48:49]
	s_add_i32 m0, s8, 0xc000
	s_waitcnt lgkmcnt(0)
	ds_read_b128 v[174:177], v231
	ds_read_b128 v[190:193], v231 offset:1024
	ds_read_b128 v[170:173], v231 offset:2048
	ds_read_b128 v[186:189], v231 offset:3072
	ds_read_b128 v[166:169], v231 offset:4096
	ds_read_b128 v[182:185], v231 offset:5120
	ds_read_b128 v[162:165], v231 offset:6144
	ds_read_b128 v[178:181], v231 offset:7168
	global_load_lds_dwordx4 v[234:235], off
	v_lshl_add_u64 v[234:235], v[224:225], 0, s[48:49]
	s_add_i32 m0, s8, 0xe000
	s_nop 0
	global_load_lds_dwordx4 v[234:235], off
	s_waitcnt vmcnt(8) lgkmcnt(0)
	s_barrier
	v_mfma_f32_16x16x32_bf16 v[126:129], v[146:149], v[174:177], v[126:129]
	v_mfma_f32_16x16x32_bf16 v[122:125], v[154:157], v[174:177], v[122:125]
	v_mfma_f32_16x16x32_bf16 v[118:121], v[146:149], v[170:173], v[118:121]
	v_mfma_f32_16x16x32_bf16 v[110:113], v[154:157], v[170:173], v[110:113]
	v_mfma_f32_16x16x32_bf16 v[102:105], v[146:149], v[166:169], v[102:105]
	v_mfma_f32_16x16x32_bf16 v[94:97], v[154:157], v[166:169], v[94:97]
	v_mfma_f32_16x16x32_bf16 v[86:89], v[146:149], v[162:165], v[86:89]
	v_mfma_f32_16x16x32_bf16 v[78:81], v[154:157], v[162:165], v[78:81]
	v_mfma_f32_16x16x32_bf16 v[126:129], v[150:153], v[190:193], v[126:129]
	v_mfma_f32_16x16x32_bf16 v[122:125], v[158:161], v[190:193], v[122:125]
	v_mfma_f32_16x16x32_bf16 v[118:121], v[150:153], v[186:189], v[118:121]
	v_mfma_f32_16x16x32_bf16 v[110:113], v[158:161], v[186:189], v[110:113]
	v_mfma_f32_16x16x32_bf16 v[102:105], v[150:153], v[182:185], v[102:105]
	v_mfma_f32_16x16x32_bf16 v[94:97], v[158:161], v[182:185], v[94:97]
	v_mfma_f32_16x16x32_bf16 v[86:89], v[150:153], v[178:181], v[86:89]
	v_mfma_f32_16x16x32_bf16 v[78:81], v[158:161], v[178:181], v[78:81]
	v_mfma_f32_16x16x32_bf16 v[114:117], v[130:133], v[174:177], v[114:117]
	v_mfma_f32_16x16x32_bf16 v[106:109], v[138:141], v[174:177], v[106:109]
	v_mfma_f32_16x16x32_bf16 v[98:101], v[130:133], v[170:173], v[98:101]
	v_mfma_f32_16x16x32_bf16 v[90:93], v[138:141], v[170:173], v[90:93]
	v_mfma_f32_16x16x32_bf16 v[82:85], v[130:133], v[166:169], v[82:85]
	v_mfma_f32_16x16x32_bf16 v[74:77], v[138:141], v[166:169], v[74:77]
	v_mfma_f32_16x16x32_bf16 v[70:73], v[130:133], v[162:165], v[70:73]
	v_mfma_f32_16x16x32_bf16 v[66:69], v[138:141], v[162:165], v[66:69]
	v_mfma_f32_16x16x32_bf16 v[114:117], v[134:137], v[190:193], v[114:117]
	v_mfma_f32_16x16x32_bf16 v[106:109], v[142:145], v[190:193], v[106:109]
	v_mfma_f32_16x16x32_bf16 v[98:101], v[134:137], v[186:189], v[98:101]
	v_mfma_f32_16x16x32_bf16 v[90:93], v[142:145], v[186:189], v[90:93]
	v_mfma_f32_16x16x32_bf16 v[82:85], v[134:137], v[182:185], v[82:85]
	v_mfma_f32_16x16x32_bf16 v[74:77], v[142:145], v[182:185], v[74:77]
	v_mfma_f32_16x16x32_bf16 v[70:73], v[134:137], v[178:181], v[70:73]
	v_mfma_f32_16x16x32_bf16 v[66:69], v[142:145], v[178:181], v[66:69]
	s_barrier
	s_andn2_b64 s[42:43], exec, s[40:41]
	s_andn2_b64 vcc, exec, s[40:41]
	s_cbranch_vccnz .LBB0_1291
	ds_read_b128 v[174:177], v231 offset:16384
	ds_read_b128 v[190:193], v231 offset:17408
	ds_read_b128 v[170:173], v231 offset:18432
	ds_read_b128 v[186:189], v231 offset:19456
	ds_read_b128 v[166:169], v231 offset:20480
	ds_read_b128 v[182:185], v231 offset:21504
	ds_read_b128 v[162:165], v231 offset:22528
	ds_read_b128 v[178:181], v231 offset:23552
.LBB0_1291:
	s_add_u32 s52, s36, s48
	s_addc_u32 s53, s37, s49
	s_add_u32 s56, s52, 0x440000
	s_addc_u32 s57, s53, 0
	s_cmp_eq_u32 s48, 0x3fc0000
	s_cselect_b64 s[58:59], -1, 0
	s_and_b64 s[52:53], s[58:59], exec
	s_cselect_b32 s53, s31, s63
	s_cselect_b32 s52, s61, s62
	s_mov_b32 m0, s9
	s_cselect_b32 s57, s19, s57
	s_cselect_b32 s56, s29, s56
	s_add_u32 s68, s52, 0x4000
	global_load_lds_dwordx4 v194, s[52:53]
	s_mov_b32 m0, s10
	s_addc_u32 s69, s53, 0
	global_load_lds_dwordx4 v196, s[52:53]
	s_mov_b32 m0, s11
	s_and_b64 vcc, exec, s[42:43]
	global_load_lds_dwordx4 v194, s[68:69]
	s_mov_b32 m0, s12
	s_nop 0
	global_load_lds_dwordx4 v196, s[68:69]
	s_waitcnt vmcnt(6) lgkmcnt(0)
	s_barrier
	s_cbranch_vccnz .LBB0_1293
	s_waitcnt lgkmcnt(0)
	v_mfma_f32_16x16x32_bf16 v[62:65], v[146:149], v[174:177], v[62:65]
	v_mfma_f32_16x16x32_bf16 v[58:61], v[154:157], v[174:177], v[58:61]
	v_mfma_f32_16x16x32_bf16 v[46:49], v[146:149], v[170:173], v[46:49]
	v_mfma_f32_16x16x32_bf16 v[42:45], v[154:157], v[170:173], v[42:45]
	v_mfma_f32_16x16x32_bf16 v[30:33], v[146:149], v[166:169], v[30:33]
	v_mfma_f32_16x16x32_bf16 v[26:29], v[154:157], v[166:169], v[26:29]
	v_mfma_f32_16x16x32_bf16 v[14:17], v[146:149], v[162:165], v[14:17]
	v_mfma_f32_16x16x32_bf16 v[10:13], v[154:157], v[162:165], v[10:13]
	v_mfma_f32_16x16x32_bf16 v[62:65], v[150:153], v[190:193], v[62:65]
	v_mfma_f32_16x16x32_bf16 v[58:61], v[158:161], v[190:193], v[58:61]
	v_mfma_f32_16x16x32_bf16 v[46:49], v[150:153], v[186:189], v[46:49]
	v_mfma_f32_16x16x32_bf16 v[42:45], v[158:161], v[186:189], v[42:45]
	v_mfma_f32_16x16x32_bf16 v[30:33], v[150:153], v[182:185], v[30:33]
	v_mfma_f32_16x16x32_bf16 v[26:29], v[158:161], v[182:185], v[26:29]
	v_mfma_f32_16x16x32_bf16 v[14:17], v[150:153], v[178:181], v[14:17]
	v_mfma_f32_16x16x32_bf16 v[10:13], v[158:161], v[178:181], v[10:13]
	v_mfma_f32_16x16x32_bf16 v[54:57], v[130:133], v[174:177], v[54:57]
	v_mfma_f32_16x16x32_bf16 v[50:53], v[138:141], v[174:177], v[50:53]
	v_mfma_f32_16x16x32_bf16 v[38:41], v[130:133], v[170:173], v[38:41]
	v_mfma_f32_16x16x32_bf16 v[34:37], v[138:141], v[170:173], v[34:37]
	v_mfma_f32_16x16x32_bf16 v[22:25], v[130:133], v[166:169], v[22:25]
	v_mfma_f32_16x16x32_bf16 v[18:21], v[138:141], v[166:169], v[18:21]
	v_mfma_f32_16x16x32_bf16 v[6:9], v[130:133], v[162:165], v[6:9]
	v_mfma_f32_16x16x32_bf16 v[2:5], v[138:141], v[162:165], v[2:5]
	v_mfma_f32_16x16x32_bf16 v[54:57], v[134:137], v[190:193], v[54:57]
	v_mfma_f32_16x16x32_bf16 v[50:53], v[142:145], v[190:193], v[50:53]
	v_mfma_f32_16x16x32_bf16 v[38:41], v[134:137], v[186:189], v[38:41]
	v_mfma_f32_16x16x32_bf16 v[34:37], v[142:145], v[186:189], v[34:37]
	v_mfma_f32_16x16x32_bf16 v[22:25], v[134:137], v[182:185], v[22:25]
	v_mfma_f32_16x16x32_bf16 v[18:21], v[142:145], v[182:185], v[18:21]
	v_mfma_f32_16x16x32_bf16 v[6:9], v[134:137], v[178:181], v[6:9]
	v_mfma_f32_16x16x32_bf16 v[2:5], v[142:145], v[178:181], v[2:5]
.LBB0_1293:
	s_and_b64 vcc, s[34:35], s[58:59]
	v_cndmask_b32_e64 v131, v221, 0, vcc
	v_cndmask_b32_e32 v130, v220, v198, vcc
	v_lshl_add_u64 v[234:235], s[56:57], 0, v[130:131]
	s_mov_b32 m0, s8
	s_nop 0
	global_load_lds_dwordx4 v194, s[56:57]
	s_mov_b32 m0, s13
	s_nop 0
	global_load_lds_dwordx4 v196, s[56:57]
	s_barrier
	v_add_u32_e32 v130, 0x18000, v229
	v_add_u32_e32 v142, 0x1c000, v229
	ds_read_b128 v[146:149], v130
	ds_read_b128 v[150:153], v130 offset:1024
	ds_read_b128 v[154:157], v130 offset:2048
	ds_read_b128 v[158:161], v130 offset:3072
	ds_read_b128 v[130:133], v142
	ds_read_b128 v[134:137], v142 offset:1024
	ds_read_b128 v[138:141], v142 offset:2048
	ds_read_b128 v[142:145], v142 offset:3072
	s_mov_b32 m0, s14
	v_lshl_add_u64 v[236:237], v[234:235], 0, v[194:195]
	s_waitcnt lgkmcnt(0)
	ds_read_b128 v[174:177], v231 offset:32768
	ds_read_b128 v[190:193], v231 offset:33792
	ds_read_b128 v[170:173], v231 offset:34816
	ds_read_b128 v[186:189], v231 offset:35840
	ds_read_b128 v[166:169], v231 offset:36864
	ds_read_b128 v[182:185], v231 offset:37888
	ds_read_b128 v[162:165], v231 offset:38912
	ds_read_b128 v[178:181], v231 offset:39936
	global_load_lds_dwordx4 v[236:237], off
	v_lshl_add_u64 v[234:235], v[234:235], 0, v[196:197]
	s_mov_b32 m0, s15
	s_nop 0
	global_load_lds_dwordx4 v[234:235], off
	s_waitcnt vmcnt(8) lgkmcnt(0)
	s_barrier
	v_mfma_f32_16x16x32_bf16 v[126:129], v[146:149], v[174:177], v[126:129]
	v_mfma_f32_16x16x32_bf16 v[122:125], v[154:157], v[174:177], v[122:125]
	v_mfma_f32_16x16x32_bf16 v[118:121], v[146:149], v[170:173], v[118:121]
	v_mfma_f32_16x16x32_bf16 v[110:113], v[154:157], v[170:173], v[110:113]
	v_mfma_f32_16x16x32_bf16 v[102:105], v[146:149], v[166:169], v[102:105]
	v_mfma_f32_16x16x32_bf16 v[94:97], v[154:157], v[166:169], v[94:97]
	v_mfma_f32_16x16x32_bf16 v[86:89], v[146:149], v[162:165], v[86:89]
	v_mfma_f32_16x16x32_bf16 v[78:81], v[154:157], v[162:165], v[78:81]
	v_mfma_f32_16x16x32_bf16 v[126:129], v[150:153], v[190:193], v[126:129]
	v_mfma_f32_16x16x32_bf16 v[122:125], v[158:161], v[190:193], v[122:125]
	v_mfma_f32_16x16x32_bf16 v[118:121], v[150:153], v[186:189], v[118:121]
	v_mfma_f32_16x16x32_bf16 v[110:113], v[158:161], v[186:189], v[110:113]
	v_mfma_f32_16x16x32_bf16 v[102:105], v[150:153], v[182:185], v[102:105]
	v_mfma_f32_16x16x32_bf16 v[94:97], v[158:161], v[182:185], v[94:97]
	v_mfma_f32_16x16x32_bf16 v[86:89], v[150:153], v[178:181], v[86:89]
	v_mfma_f32_16x16x32_bf16 v[78:81], v[158:161], v[178:181], v[78:81]
	v_mfma_f32_16x16x32_bf16 v[114:117], v[130:133], v[174:177], v[114:117]
	v_mfma_f32_16x16x32_bf16 v[106:109], v[138:141], v[174:177], v[106:109]
	v_mfma_f32_16x16x32_bf16 v[98:101], v[130:133], v[170:173], v[98:101]
	v_mfma_f32_16x16x32_bf16 v[90:93], v[138:141], v[170:173], v[90:93]
	v_mfma_f32_16x16x32_bf16 v[82:85], v[130:133], v[166:169], v[82:85]
	v_mfma_f32_16x16x32_bf16 v[74:77], v[138:141], v[166:169], v[74:77]
	v_mfma_f32_16x16x32_bf16 v[70:73], v[130:133], v[162:165], v[70:73]
	v_mfma_f32_16x16x32_bf16 v[66:69], v[138:141], v[162:165], v[66:69]
	v_mfma_f32_16x16x32_bf16 v[114:117], v[134:137], v[190:193], v[114:117]
	v_mfma_f32_16x16x32_bf16 v[106:109], v[142:145], v[190:193], v[106:109]
	v_mfma_f32_16x16x32_bf16 v[98:101], v[134:137], v[186:189], v[98:101]
	v_mfma_f32_16x16x32_bf16 v[90:93], v[142:145], v[186:189], v[90:93]
	v_mfma_f32_16x16x32_bf16 v[82:85], v[134:137], v[182:185], v[82:85]
	v_mfma_f32_16x16x32_bf16 v[74:77], v[142:145], v[182:185], v[74:77]
	v_mfma_f32_16x16x32_bf16 v[70:73], v[134:137], v[178:181], v[70:73]
	v_mfma_f32_16x16x32_bf16 v[66:69], v[142:145], v[178:181], v[66:69]
	s_barrier
	s_and_b64 vcc, exec, s[42:43]
	s_cbranch_vccnz .LBB0_1295
	ds_read_b128 v[174:177], v231 offset:49152
	ds_read_b128 v[190:193], v231 offset:50176
	ds_read_b128 v[170:173], v231 offset:51200
	ds_read_b128 v[186:189], v231 offset:52224
	ds_read_b128 v[166:169], v231 offset:53248
	ds_read_b128 v[182:185], v231 offset:54272
	ds_read_b128 v[162:165], v231 offset:55296
	ds_read_b128 v[178:181], v231 offset:56320
.LBB0_1295:
	s_add_u32 s58, s52, 0x40000
	s_addc_u32 s59, s53, 0
	s_add_u32 s56, s56, 0x220000
	s_addc_u32 s57, s57, 0
	s_mov_b32 m0, s16
	s_add_u32 s52, s52, 0x44000
	global_load_lds_dwordx4 v194, s[58:59]
	s_mov_b32 m0, s17
	s_addc_u32 s53, s53, 0
	global_load_lds_dwordx4 v196, s[58:59]
	s_mov_b32 m0, s55
	s_and_b64 vcc, exec, s[42:43]
	global_load_lds_dwordx4 v194, s[52:53]
	s_mov_b32 m0, s60
	s_nop 0
	global_load_lds_dwordx4 v196, s[52:53]
	s_waitcnt vmcnt(6) lgkmcnt(0)
	s_barrier
	s_cbranch_vccnz .LBB0_1288
	s_waitcnt lgkmcnt(0)
	v_mfma_f32_16x16x32_bf16 v[62:65], v[146:149], v[174:177], v[62:65]
	v_mfma_f32_16x16x32_bf16 v[58:61], v[154:157], v[174:177], v[58:61]
	v_mfma_f32_16x16x32_bf16 v[46:49], v[146:149], v[170:173], v[46:49]
	v_mfma_f32_16x16x32_bf16 v[42:45], v[154:157], v[170:173], v[42:45]
	v_mfma_f32_16x16x32_bf16 v[30:33], v[146:149], v[166:169], v[30:33]
	v_mfma_f32_16x16x32_bf16 v[26:29], v[154:157], v[166:169], v[26:29]
	v_mfma_f32_16x16x32_bf16 v[14:17], v[146:149], v[162:165], v[14:17]
	v_mfma_f32_16x16x32_bf16 v[10:13], v[154:157], v[162:165], v[10:13]
	v_mfma_f32_16x16x32_bf16 v[62:65], v[150:153], v[190:193], v[62:65]
	v_mfma_f32_16x16x32_bf16 v[58:61], v[158:161], v[190:193], v[58:61]
	v_mfma_f32_16x16x32_bf16 v[46:49], v[150:153], v[186:189], v[46:49]
	v_mfma_f32_16x16x32_bf16 v[42:45], v[158:161], v[186:189], v[42:45]
	v_mfma_f32_16x16x32_bf16 v[30:33], v[150:153], v[182:185], v[30:33]
	v_mfma_f32_16x16x32_bf16 v[26:29], v[158:161], v[182:185], v[26:29]
	v_mfma_f32_16x16x32_bf16 v[14:17], v[150:153], v[178:181], v[14:17]
	v_mfma_f32_16x16x32_bf16 v[10:13], v[158:161], v[178:181], v[10:13]
	v_mfma_f32_16x16x32_bf16 v[54:57], v[130:133], v[174:177], v[54:57]
	v_mfma_f32_16x16x32_bf16 v[50:53], v[138:141], v[174:177], v[50:53]
	v_mfma_f32_16x16x32_bf16 v[38:41], v[130:133], v[170:173], v[38:41]
	v_mfma_f32_16x16x32_bf16 v[34:37], v[138:141], v[170:173], v[34:37]
	v_mfma_f32_16x16x32_bf16 v[22:25], v[130:133], v[166:169], v[22:25]
	v_mfma_f32_16x16x32_bf16 v[18:21], v[138:141], v[166:169], v[18:21]
	v_mfma_f32_16x16x32_bf16 v[6:9], v[130:133], v[162:165], v[6:9]
	v_mfma_f32_16x16x32_bf16 v[2:5], v[138:141], v[162:165], v[2:5]
	v_mfma_f32_16x16x32_bf16 v[54:57], v[134:137], v[190:193], v[54:57]
	v_mfma_f32_16x16x32_bf16 v[50:53], v[142:145], v[190:193], v[50:53]
	v_mfma_f32_16x16x32_bf16 v[38:41], v[134:137], v[186:189], v[38:41]
	v_mfma_f32_16x16x32_bf16 v[34:37], v[142:145], v[186:189], v[34:37]
	v_mfma_f32_16x16x32_bf16 v[22:25], v[134:137], v[182:185], v[22:25]
	v_mfma_f32_16x16x32_bf16 v[18:21], v[142:145], v[182:185], v[18:21]
	v_mfma_f32_16x16x32_bf16 v[6:9], v[134:137], v[178:181], v[6:9]
	v_mfma_f32_16x16x32_bf16 v[2:5], v[142:145], v[178:181], v[2:5]
	s_branch .LBB0_1288

.LBB0_1611:
	s_mov_b32 m0, s54
	s_nop 0
	global_load_lds_dwordx4 v194, s[52:53]
	s_mov_b32 m0, s55
	s_nop 0
	global_load_lds_dwordx4 v196, s[52:53]
	s_barrier
	s_add_i32 s62, s62, 2
	s_add_u32 s60, s60, 0x80000
	s_addc_u32 s61, s61, 0
	s_add_u32 s48, s48, 0x440000
	s_addc_u32 s49, s49, 0
	s_cmp_gt_u32 s62, 29
	s_cbranch_scc1 .LBB0_1620
.LBB0_1612:
	v_add_u32_e32 v1, 0x10000, v232
	ds_read_b128 v[146:149], v1
	ds_read_b128 v[150:153], v1 offset:1024
	ds_read_b128 v[154:157], v1 offset:2048
	ds_read_b128 v[158:161], v1 offset:3072
	v_add_u32_e32 v1, 0x14000, v232
	ds_read_b128 v[130:133], v1
	ds_read_b128 v[134:137], v1 offset:1024
	ds_read_b128 v[138:141], v1 offset:2048
	ds_read_b128 v[142:145], v1 offset:3072
	v_lshl_add_u64 v[236:237], v[226:227], 0, s[48:49]
	s_add_i32 m0, s9, 0xc000
	s_waitcnt lgkmcnt(0)
	ds_read_b128 v[174:177], v233
	ds_read_b128 v[190:193], v233 offset:1024
	ds_read_b128 v[170:173], v233 offset:2048
	ds_read_b128 v[186:189], v233 offset:3072
	ds_read_b128 v[166:169], v233 offset:4096
	ds_read_b128 v[182:185], v233 offset:5120
	ds_read_b128 v[162:165], v233 offset:6144
	ds_read_b128 v[178:181], v233 offset:7168
	global_load_lds_dwordx4 v[236:237], off
	v_lshl_add_u64 v[236:237], v[228:229], 0, s[48:49]
	s_add_i32 m0, s9, 0xe000
	s_nop 0
	global_load_lds_dwordx4 v[236:237], off
	s_waitcnt vmcnt(8) lgkmcnt(0)
	s_barrier
	v_mfma_f32_16x16x32_bf16 v[126:129], v[146:149], v[174:177], v[126:129]
	v_mfma_f32_16x16x32_bf16 v[122:125], v[154:157], v[174:177], v[122:125]
	v_mfma_f32_16x16x32_bf16 v[118:121], v[146:149], v[170:173], v[118:121]
	v_mfma_f32_16x16x32_bf16 v[110:113], v[154:157], v[170:173], v[110:113]
	v_mfma_f32_16x16x32_bf16 v[102:105], v[146:149], v[166:169], v[102:105]
	v_mfma_f32_16x16x32_bf16 v[94:97], v[154:157], v[166:169], v[94:97]
	v_mfma_f32_16x16x32_bf16 v[86:89], v[146:149], v[162:165], v[86:89]
	v_mfma_f32_16x16x32_bf16 v[78:81], v[154:157], v[162:165], v[78:81]
	v_mfma_f32_16x16x32_bf16 v[126:129], v[150:153], v[190:193], v[126:129]
	v_mfma_f32_16x16x32_bf16 v[122:125], v[158:161], v[190:193], v[122:125]
	v_mfma_f32_16x16x32_bf16 v[118:121], v[150:153], v[186:189], v[118:121]
	v_mfma_f32_16x16x32_bf16 v[110:113], v[158:161], v[186:189], v[110:113]
	v_mfma_f32_16x16x32_bf16 v[102:105], v[150:153], v[182:185], v[102:105]
	v_mfma_f32_16x16x32_bf16 v[94:97], v[158:161], v[182:185], v[94:97]
	v_mfma_f32_16x16x32_bf16 v[86:89], v[150:153], v[178:181], v[86:89]
	v_mfma_f32_16x16x32_bf16 v[78:81], v[158:161], v[178:181], v[78:81]
	v_mfma_f32_16x16x32_bf16 v[114:117], v[130:133], v[174:177], v[114:117]
	v_mfma_f32_16x16x32_bf16 v[106:109], v[138:141], v[174:177], v[106:109]
	v_mfma_f32_16x16x32_bf16 v[98:101], v[130:133], v[170:173], v[98:101]
	v_mfma_f32_16x16x32_bf16 v[90:93], v[138:141], v[170:173], v[90:93]
	v_mfma_f32_16x16x32_bf16 v[82:85], v[130:133], v[166:169], v[82:85]
	v_mfma_f32_16x16x32_bf16 v[74:77], v[138:141], v[166:169], v[74:77]
	v_mfma_f32_16x16x32_bf16 v[70:73], v[130:133], v[162:165], v[70:73]
	v_mfma_f32_16x16x32_bf16 v[66:69], v[138:141], v[162:165], v[66:69]
	v_mfma_f32_16x16x32_bf16 v[114:117], v[134:137], v[190:193], v[114:117]
	v_mfma_f32_16x16x32_bf16 v[106:109], v[142:145], v[190:193], v[106:109]
	v_mfma_f32_16x16x32_bf16 v[98:101], v[134:137], v[186:189], v[98:101]
	v_mfma_f32_16x16x32_bf16 v[90:93], v[142:145], v[186:189], v[90:93]
	v_mfma_f32_16x16x32_bf16 v[82:85], v[134:137], v[182:185], v[82:85]
	v_mfma_f32_16x16x32_bf16 v[74:77], v[142:145], v[182:185], v[74:77]
	v_mfma_f32_16x16x32_bf16 v[70:73], v[134:137], v[178:181], v[70:73]
	v_mfma_f32_16x16x32_bf16 v[66:69], v[142:145], v[178:181], v[66:69]
	s_barrier
	s_andn2_b64 s[42:43], exec, s[40:41]
	s_andn2_b64 vcc, exec, s[40:41]
	s_cbranch_vccnz .LBB0_1614
	ds_read_b128 v[174:177], v233 offset:16384
	ds_read_b128 v[190:193], v233 offset:17408
	ds_read_b128 v[170:173], v233 offset:18432
	ds_read_b128 v[186:189], v233 offset:19456
	ds_read_b128 v[166:169], v233 offset:20480
	ds_read_b128 v[182:185], v233 offset:21504
	ds_read_b128 v[162:165], v233 offset:22528
	ds_read_b128 v[178:181], v233 offset:23552
.LBB0_1614:
	s_add_u32 s50, s46, s48
	s_addc_u32 s51, s47, s49
	s_add_u32 s52, s50, 0x440000
	s_addc_u32 s53, s51, 0
	s_cmp_eq_u32 s48, 0x3fc0000
	s_cselect_b64 s[56:57], -1, 0
	s_and_b64 s[50:51], s[56:57], exec
	s_cselect_b32 s51, s31, s61
	s_cselect_b32 s50, s35, s60
	s_mov_b32 m0, s10
	s_cselect_b32 s53, s19, s53
	s_cselect_b32 s52, s20, s52
	s_add_u32 s68, s50, 0x4000
	global_load_lds_dwordx4 v194, s[50:51]
	s_mov_b32 m0, s11
	s_addc_u32 s69, s51, 0
	global_load_lds_dwordx4 v196, s[50:51]
	s_mov_b32 m0, s12
	s_and_b64 vcc, exec, s[42:43]
	global_load_lds_dwordx4 v194, s[68:69]
	s_mov_b32 m0, s13
	s_nop 0
	global_load_lds_dwordx4 v196, s[68:69]
	s_waitcnt vmcnt(6) lgkmcnt(0)
	s_barrier
	s_cbranch_vccnz .LBB0_1616
	s_waitcnt lgkmcnt(0)
	v_mfma_f32_16x16x32_bf16 v[62:65], v[146:149], v[174:177], v[62:65]
	v_mfma_f32_16x16x32_bf16 v[58:61], v[154:157], v[174:177], v[58:61]
	v_mfma_f32_16x16x32_bf16 v[46:49], v[146:149], v[170:173], v[46:49]
	v_mfma_f32_16x16x32_bf16 v[42:45], v[154:157], v[170:173], v[42:45]
	v_mfma_f32_16x16x32_bf16 v[30:33], v[146:149], v[166:169], v[30:33]
	v_mfma_f32_16x16x32_bf16 v[26:29], v[154:157], v[166:169], v[26:29]
	v_mfma_f32_16x16x32_bf16 v[14:17], v[146:149], v[162:165], v[14:17]
	v_mfma_f32_16x16x32_bf16 v[10:13], v[154:157], v[162:165], v[10:13]
	v_mfma_f32_16x16x32_bf16 v[62:65], v[150:153], v[190:193], v[62:65]
	v_mfma_f32_16x16x32_bf16 v[58:61], v[158:161], v[190:193], v[58:61]
	v_mfma_f32_16x16x32_bf16 v[46:49], v[150:153], v[186:189], v[46:49]
	v_mfma_f32_16x16x32_bf16 v[42:45], v[158:161], v[186:189], v[42:45]
	v_mfma_f32_16x16x32_bf16 v[30:33], v[150:153], v[182:185], v[30:33]
	v_mfma_f32_16x16x32_bf16 v[26:29], v[158:161], v[182:185], v[26:29]
	v_mfma_f32_16x16x32_bf16 v[14:17], v[150:153], v[178:181], v[14:17]
	v_mfma_f32_16x16x32_bf16 v[10:13], v[158:161], v[178:181], v[10:13]
	v_mfma_f32_16x16x32_bf16 v[54:57], v[130:133], v[174:177], v[54:57]
	v_mfma_f32_16x16x32_bf16 v[50:53], v[138:141], v[174:177], v[50:53]
	v_mfma_f32_16x16x32_bf16 v[38:41], v[130:133], v[170:173], v[38:41]
	v_mfma_f32_16x16x32_bf16 v[34:37], v[138:141], v[170:173], v[34:37]
	v_mfma_f32_16x16x32_bf16 v[22:25], v[130:133], v[166:169], v[22:25]
	v_mfma_f32_16x16x32_bf16 v[18:21], v[138:141], v[166:169], v[18:21]
	v_mfma_f32_16x16x32_bf16 v[6:9], v[130:133], v[162:165], v[6:9]
	v_mfma_f32_16x16x32_bf16 v[2:5], v[138:141], v[162:165], v[2:5]
	v_mfma_f32_16x16x32_bf16 v[54:57], v[134:137], v[190:193], v[54:57]
	v_mfma_f32_16x16x32_bf16 v[50:53], v[142:145], v[190:193], v[50:53]
	v_mfma_f32_16x16x32_bf16 v[38:41], v[134:137], v[186:189], v[38:41]
	v_mfma_f32_16x16x32_bf16 v[34:37], v[142:145], v[186:189], v[34:37]
	v_mfma_f32_16x16x32_bf16 v[22:25], v[134:137], v[182:185], v[22:25]
	v_mfma_f32_16x16x32_bf16 v[18:21], v[142:145], v[182:185], v[18:21]
	v_mfma_f32_16x16x32_bf16 v[6:9], v[134:137], v[178:181], v[6:9]
	v_mfma_f32_16x16x32_bf16 v[2:5], v[142:145], v[178:181], v[2:5]
.LBB0_1616:
	s_and_b64 vcc, s[38:39], s[56:57]
	v_cndmask_b32_e64 v131, v225, 0, vcc
	v_cndmask_b32_e32 v130, v224, v198, vcc
	v_lshl_add_u64 v[236:237], s[52:53], 0, v[130:131]
	s_mov_b32 m0, s9
	s_nop 0
	global_load_lds_dwordx4 v194, s[52:53]
	s_mov_b32 m0, s14
	s_nop 0
	global_load_lds_dwordx4 v196, s[52:53]
	s_barrier
	v_add_u32_e32 v1, 0x18000, v232
	ds_read_b128 v[146:149], v1
	ds_read_b128 v[150:153], v1 offset:1024
	ds_read_b128 v[154:157], v1 offset:2048
	ds_read_b128 v[158:161], v1 offset:3072
	v_add_u32_e32 v1, 0x1c000, v232
	ds_read_b128 v[130:133], v1
	ds_read_b128 v[134:137], v1 offset:1024
	ds_read_b128 v[138:141], v1 offset:2048
	ds_read_b128 v[142:145], v1 offset:3072
	s_mov_b32 m0, s15
	v_lshl_add_u64 v[238:239], v[236:237], 0, v[194:195]
	s_waitcnt lgkmcnt(0)
	ds_read_b128 v[174:177], v233 offset:32768
	ds_read_b128 v[190:193], v233 offset:33792
	ds_read_b128 v[170:173], v233 offset:34816
	ds_read_b128 v[186:189], v233 offset:35840
	ds_read_b128 v[166:169], v233 offset:36864
	ds_read_b128 v[182:185], v233 offset:37888
	ds_read_b128 v[162:165], v233 offset:38912
	ds_read_b128 v[178:181], v233 offset:39936
	global_load_lds_dwordx4 v[238:239], off
	v_lshl_add_u64 v[236:237], v[236:237], 0, v[196:197]
	s_mov_b32 m0, s16
	s_nop 0
	global_load_lds_dwordx4 v[236:237], off
	s_waitcnt vmcnt(8) lgkmcnt(0)
	s_barrier
	v_mfma_f32_16x16x32_bf16 v[126:129], v[146:149], v[174:177], v[126:129]
	v_mfma_f32_16x16x32_bf16 v[122:125], v[154:157], v[174:177], v[122:125]
	v_mfma_f32_16x16x32_bf16 v[118:121], v[146:149], v[170:173], v[118:121]
	v_mfma_f32_16x16x32_bf16 v[110:113], v[154:157], v[170:173], v[110:113]
	v_mfma_f32_16x16x32_bf16 v[102:105], v[146:149], v[166:169], v[102:105]
	v_mfma_f32_16x16x32_bf16 v[94:97], v[154:157], v[166:169], v[94:97]
	v_mfma_f32_16x16x32_bf16 v[86:89], v[146:149], v[162:165], v[86:89]
	v_mfma_f32_16x16x32_bf16 v[78:81], v[154:157], v[162:165], v[78:81]
	v_mfma_f32_16x16x32_bf16 v[126:129], v[150:153], v[190:193], v[126:129]
	v_mfma_f32_16x16x32_bf16 v[122:125], v[158:161], v[190:193], v[122:125]
	v_mfma_f32_16x16x32_bf16 v[118:121], v[150:153], v[186:189], v[118:121]
	v_mfma_f32_16x16x32_bf16 v[110:113], v[158:161], v[186:189], v[110:113]
	v_mfma_f32_16x16x32_bf16 v[102:105], v[150:153], v[182:185], v[102:105]
	v_mfma_f32_16x16x32_bf16 v[94:97], v[158:161], v[182:185], v[94:97]
	v_mfma_f32_16x16x32_bf16 v[86:89], v[150:153], v[178:181], v[86:89]
	v_mfma_f32_16x16x32_bf16 v[78:81], v[158:161], v[178:181], v[78:81]
	v_mfma_f32_16x16x32_bf16 v[114:117], v[130:133], v[174:177], v[114:117]
	v_mfma_f32_16x16x32_bf16 v[106:109], v[138:141], v[174:177], v[106:109]
	v_mfma_f32_16x16x32_bf16 v[98:101], v[130:133], v[170:173], v[98:101]
	v_mfma_f32_16x16x32_bf16 v[90:93], v[138:141], v[170:173], v[90:93]
	v_mfma_f32_16x16x32_bf16 v[82:85], v[130:133], v[166:169], v[82:85]
	v_mfma_f32_16x16x32_bf16 v[74:77], v[138:141], v[166:169], v[74:77]
	v_mfma_f32_16x16x32_bf16 v[70:73], v[130:133], v[162:165], v[70:73]
	v_mfma_f32_16x16x32_bf16 v[66:69], v[138:141], v[162:165], v[66:69]
	v_mfma_f32_16x16x32_bf16 v[114:117], v[134:137], v[190:193], v[114:117]
	v_mfma_f32_16x16x32_bf16 v[106:109], v[142:145], v[190:193], v[106:109]
	v_mfma_f32_16x16x32_bf16 v[98:101], v[134:137], v[186:189], v[98:101]
	v_mfma_f32_16x16x32_bf16 v[90:93], v[142:145], v[186:189], v[90:93]
	v_mfma_f32_16x16x32_bf16 v[82:85], v[134:137], v[182:185], v[82:85]
	v_mfma_f32_16x16x32_bf16 v[74:77], v[142:145], v[182:185], v[74:77]
	v_mfma_f32_16x16x32_bf16 v[70:73], v[134:137], v[178:181], v[70:73]
	v_mfma_f32_16x16x32_bf16 v[66:69], v[142:145], v[178:181], v[66:69]
	s_barrier
	s_and_b64 vcc, exec, s[42:43]
	s_cbranch_vccnz .LBB0_1618
	ds_read_b128 v[174:177], v233 offset:49152
	ds_read_b128 v[190:193], v233 offset:50176
	ds_read_b128 v[170:173], v233 offset:51200
	ds_read_b128 v[186:189], v233 offset:52224
	ds_read_b128 v[166:169], v233 offset:53248
	ds_read_b128 v[182:185], v233 offset:54272
	ds_read_b128 v[162:165], v233 offset:55296
	ds_read_b128 v[178:181], v233 offset:56320
.LBB0_1618:
	s_add_u32 s56, s50, 0x40000
	s_addc_u32 s57, s51, 0
	s_add_u32 s52, s52, 0x220000
	s_addc_u32 s53, s53, 0
	s_mov_b32 m0, s17
	s_add_u32 s50, s50, 0x44000
	global_load_lds_dwordx4 v194, s[56:57]
	s_mov_b32 m0, s29
	s_addc_u32 s51, s51, 0
	global_load_lds_dwordx4 v196, s[56:57]
	s_mov_b32 m0, s58
	s_and_b64 vcc, exec, s[42:43]
	global_load_lds_dwordx4 v194, s[50:51]
	s_mov_b32 m0, s59
	s_nop 0
	global_load_lds_dwordx4 v196, s[50:51]
	s_waitcnt vmcnt(6) lgkmcnt(0)
	s_barrier
	s_cbranch_vccnz .LBB0_1611
	s_waitcnt lgkmcnt(0)
	v_mfma_f32_16x16x32_bf16 v[62:65], v[146:149], v[174:177], v[62:65]
	v_mfma_f32_16x16x32_bf16 v[58:61], v[154:157], v[174:177], v[58:61]
	v_mfma_f32_16x16x32_bf16 v[46:49], v[146:149], v[170:173], v[46:49]
	v_mfma_f32_16x16x32_bf16 v[42:45], v[154:157], v[170:173], v[42:45]
	v_mfma_f32_16x16x32_bf16 v[30:33], v[146:149], v[166:169], v[30:33]
	v_mfma_f32_16x16x32_bf16 v[26:29], v[154:157], v[166:169], v[26:29]
	v_mfma_f32_16x16x32_bf16 v[14:17], v[146:149], v[162:165], v[14:17]
	v_mfma_f32_16x16x32_bf16 v[10:13], v[154:157], v[162:165], v[10:13]
	v_mfma_f32_16x16x32_bf16 v[62:65], v[150:153], v[190:193], v[62:65]
	v_mfma_f32_16x16x32_bf16 v[58:61], v[158:161], v[190:193], v[58:61]
	v_mfma_f32_16x16x32_bf16 v[46:49], v[150:153], v[186:189], v[46:49]
	v_mfma_f32_16x16x32_bf16 v[42:45], v[158:161], v[186:189], v[42:45]
	v_mfma_f32_16x16x32_bf16 v[30:33], v[150:153], v[182:185], v[30:33]
	v_mfma_f32_16x16x32_bf16 v[26:29], v[158:161], v[182:185], v[26:29]
	v_mfma_f32_16x16x32_bf16 v[14:17], v[150:153], v[178:181], v[14:17]
	v_mfma_f32_16x16x32_bf16 v[10:13], v[158:161], v[178:181], v[10:13]
	v_mfma_f32_16x16x32_bf16 v[54:57], v[130:133], v[174:177], v[54:57]
	v_mfma_f32_16x16x32_bf16 v[50:53], v[138:141], v[174:177], v[50:53]
	v_mfma_f32_16x16x32_bf16 v[38:41], v[130:133], v[170:173], v[38:41]
	v_mfma_f32_16x16x32_bf16 v[34:37], v[138:141], v[170:173], v[34:37]
	v_mfma_f32_16x16x32_bf16 v[22:25], v[130:133], v[166:169], v[22:25]
	v_mfma_f32_16x16x32_bf16 v[18:21], v[138:141], v[166:169], v[18:21]
	v_mfma_f32_16x16x32_bf16 v[6:9], v[130:133], v[162:165], v[6:9]
	v_mfma_f32_16x16x32_bf16 v[2:5], v[138:141], v[162:165], v[2:5]
	v_mfma_f32_16x16x32_bf16 v[54:57], v[134:137], v[190:193], v[54:57]
	v_mfma_f32_16x16x32_bf16 v[50:53], v[142:145], v[190:193], v[50:53]
	v_mfma_f32_16x16x32_bf16 v[38:41], v[134:137], v[186:189], v[38:41]
	v_mfma_f32_16x16x32_bf16 v[34:37], v[142:145], v[186:189], v[34:37]
	v_mfma_f32_16x16x32_bf16 v[22:25], v[134:137], v[182:185], v[22:25]
	v_mfma_f32_16x16x32_bf16 v[18:21], v[142:145], v[182:185], v[18:21]
	v_mfma_f32_16x16x32_bf16 v[6:9], v[134:137], v[178:181], v[6:9]
	v_mfma_f32_16x16x32_bf16 v[2:5], v[142:145], v[178:181], v[2:5]
	s_branch .LBB0_1611
